# stack E + GEMM epilogue global loads hoisted to epilogue start (EpiResid bf16 P8/P13/P16 base rows, EpiSwiglu P7/P15 rowscale)
# speedup vs baseline: 1.0056x; 1.0056x over previous
.LBB0_627:
	v_lshl_add_u32 v152, s0, 8, v154
	v_ashrrev_i32_e32 v153, 31, v152
	v_lshlrev_b64 v[150:151], 6, v[152:153]
	v_lshl_add_u64 v[150:151], v[140:141], 0, v[150:151]
	global_load_dwordx4 v[164:167], v[150:151], off
	global_load_dwordx4 v[188:191], v[150:151], off offset:1024
	global_load_dwordx4 v[192:195], v[150:151], off offset:2048
	global_load_dwordx4 v[196:199], v[150:151], off offset:3072
	v_mov_b32_e32 v216, 0x2000
	v_mov_b32_e32 v217, 0
	v_lshl_add_u64 v[216:217], v[150:151], 0, v[216:217]
	global_load_dwordx4 v[200:203], v[216:217], off
	global_load_dwordx4 v[204:207], v[216:217], off offset:1024
	global_load_dwordx4 v[208:211], v[216:217], off offset:2048
	global_load_dwordx4 v[212:215], v[216:217], off offset:3072
	v_and_b32_e32 v163, 64, v161
	v_xor_b32_e32 v153, 16, v161
	v_pk_mul_f32 v[170:171], v[114:115], v[122:123]
	v_add_u32_e32 v122, 64, v163
	v_cmp_lt_i32_e32 vcc, v153, v122
	v_pk_mul_f32 v[172:173], v[112:113], v[120:121]
	v_xor_b32_e32 v174, 32, v161
	v_cndmask_b32_e32 v120, v161, v153, vcc
	v_lshlrev_b32_e32 v123, 2, v120
	v_cmp_lt_i32_e32 vcc, v174, v122
	v_pk_mul_f32 v[126:127], v[118:119], v[126:127]
	v_pk_mul_f32 v[124:125], v[116:117], v[124:125]
	v_cndmask_b32_e32 v122, v161, v174, vcc
	v_lshlrev_b32_e32 v122, 2, v122
	v_lshl_or_b32 v168, s1, 7, v156
	v_ashrrev_i32_e32 v169, 31, v168
	v_mov_b64_e32 v[150:151], s[10:11]
	v_pk_mul_f32 v[110:111], v[102:103], v[110:111]
	v_pk_mul_f32 v[108:109], v[100:101], v[108:109]
	v_pk_mul_f32 v[106:107], v[98:99], v[106:107]
	v_pk_mul_f32 v[104:105], v[96:97], v[104:105]
	v_pk_mul_f32 v[94:95], v[86:87], v[94:95]
	v_pk_mul_f32 v[92:93], v[84:85], v[92:93]
	v_pk_mul_f32 v[90:91], v[82:83], v[90:91]
	v_pk_mul_f32 v[88:89], v[80:81], v[88:89]
	v_pk_mul_f32 v[78:79], v[70:71], v[78:79]
	v_pk_mul_f32 v[76:77], v[68:69], v[76:77]
	v_pk_mul_f32 v[74:75], v[66:67], v[74:75]
	v_pk_mul_f32 v[72:73], v[64:65], v[72:73]
	v_pk_mul_f32 v[62:63], v[54:55], v[62:63]
	v_pk_mul_f32 v[60:61], v[52:53], v[60:61]
	v_pk_mul_f32 v[58:59], v[50:51], v[58:59]
	v_pk_mul_f32 v[56:57], v[48:49], v[56:57]
	v_pk_mul_f32 v[46:47], v[38:39], v[46:47]
	v_pk_mul_f32 v[44:45], v[36:37], v[44:45]
	v_pk_mul_f32 v[42:43], v[34:35], v[42:43]
	v_pk_mul_f32 v[40:41], v[32:33], v[40:41]
	v_pk_mul_f32 v[30:31], v[22:23], v[30:31]
	v_pk_mul_f32 v[28:29], v[20:21], v[28:29]
	v_pk_mul_f32 v[26:27], v[18:19], v[26:27]
	v_pk_mul_f32 v[24:25], v[16:17], v[24:25]
	v_pk_mul_f32 v[14:15], v[6:7], v[14:15]
	v_pk_mul_f32 v[12:13], v[4:5], v[12:13]
	v_pk_mul_f32 v[10:11], v[2:3], v[10:11]
	v_pk_mul_f32 v[8:9], v[0:1], v[8:9]
	s_waitcnt vmcnt(0)
	v_mov_b32_e32 v120, v165
	v_mov_b32_e32 v121, v166
	v_mov_b32_e32 v165, v167
	v_pk_add_f32 v[120:121], v[120:121], v[164:165]
	v_or_b32_e32 v166, 16, v152
	v_add_f32_e32 v120, v120, v121
	v_mov_b32_e32 v121, v120
	s_nop 1
	v_permlane16_swap_b32_e32 v120, v121
	v_ashrrev_i32_e32 v167, 31, v166
	v_mad_i64_i32 v[164:165], s[0:1], v152, s49, v[150:151]
	s_waitcnt lgkmcnt(0)
	v_add_f32_e32 v153, v120, v121
	v_mov_b32_e32 v163, v153
	s_nop 1
	v_permlane32_swap_b32_e32 v153, v163
	v_lshlrev_b64 v[120:121], 1, v[168:169]
	v_lshlrev_b64 v[168:169], 6, v[166:167]
	v_lshl_add_u64 v[164:165], v[164:165], 0, v[120:121]
	v_lshl_add_u64 v[168:169], v[140:141], 0, v[168:169]
	s_waitcnt lgkmcnt(0)
	v_add_f32_e32 v153, v153, v163
	v_fmamk_f32 v153, v153, 0x3a800000, v162
	v_mul_f32_e32 v163, 0x4b800000, v153
	v_cmp_gt_f32_e32 vcc, s52, v153
	s_nop 1
	v_cndmask_b32_e32 v153, v153, v163, vcc
	v_rsq_f32_e32 v153, v153
	s_nop 0
	v_mul_f32_e32 v163, 0x45800000, v153
	v_cndmask_b32_e32 v153, v153, v163, vcc
	v_mul_f32_e32 v163, 0xbfb8aa3b, v153
	v_mul_f32_e32 v116, v116, v163
	v_mul_f32_e32 v117, v117, v163
	v_mul_f32_e32 v118, v118, v163
	v_mul_f32_e32 v119, v119, v163
	v_mul_f32_e32 v112, v112, v163
	v_mul_f32_e32 v113, v113, v163
	v_mul_f32_e32 v114, v114, v163
	v_mul_f32_e32 v115, v115, v163
	v_exp_f32_e32 v116, v116
	v_exp_f32_e32 v117, v117
	v_exp_f32_e32 v118, v118
	v_exp_f32_e32 v119, v119
	v_exp_f32_e32 v112, v112
	v_exp_f32_e32 v113, v113
	v_exp_f32_e32 v114, v114
	v_exp_f32_e32 v115, v115
	v_mul_f32_e32 v174, v153, v153
	v_add_f32_e32 v116, 1.0, v116
	v_add_f32_e32 v117, 1.0, v117
	v_add_f32_e32 v118, 1.0, v118
	v_add_f32_e32 v119, 1.0, v119
	v_add_f32_e32 v153, 1.0, v112
	v_add_f32_e32 v163, 1.0, v113
	v_add_f32_e32 v167, 1.0, v114
	v_add_f32_e32 v175, 1.0, v115
	v_rcp_f32_e32 v112, v116
	v_rcp_f32_e32 v113, v117
	v_rcp_f32_e32 v114, v118
	v_rcp_f32_e32 v115, v119
	v_rcp_f32_e32 v116, v153
	v_rcp_f32_e32 v117, v163
	v_rcp_f32_e32 v118, v167
	v_rcp_f32_e32 v119, v175
	v_pk_mul_f32 v[112:113], v[174:175], v[112:113] op_sel_hi:[0,1]
	v_pk_mul_f32 v[114:115], v[174:175], v[114:115] op_sel_hi:[0,1]
	v_pk_mul_f32 v[116:117], v[174:175], v[116:117] op_sel_hi:[0,1]
	v_pk_mul_f32 v[118:119], v[174:175], v[118:119] op_sel_hi:[0,1]
	v_pk_mul_f32 v[112:113], v[124:125], v[112:113]
	v_pk_mul_f32 v[114:115], v[126:127], v[114:115]
	v_pk_mul_f32 v[116:117], v[172:173], v[116:117]
	v_pk_mul_f32 v[118:119], v[170:171], v[118:119]
	v_cvt_pk_bf16_f32 v112, v112, v113
	v_cvt_pk_bf16_f32 v113, v114, v115
	v_cvt_pk_bf16_f32 v114, v116, v117
	v_cvt_pk_bf16_f32 v115, v118, v119
	global_store_dwordx4 v[164:165], v[112:115], off
	s_nop 1
	v_mov_b32_e32 v112, v188
	v_mov_b32_e32 v113, v189
	v_mov_b32_e32 v114, v190
	v_mov_b32_e32 v115, v191
	v_mov_b32_e32 v116, v113
	v_mov_b32_e32 v117, v114
	v_mov_b32_e32 v113, v115
	v_pk_add_f32 v[112:113], v[116:117], v[112:113]
	v_mad_i64_i32 v[114:115], s[0:1], v166, s49, v[150:151]
	v_add_f32_e32 v112, v112, v113
	v_mov_b32_e32 v113, v112
	s_nop 1
	v_permlane16_swap_b32_e32 v112, v113
	v_lshl_add_u64 v[114:115], v[114:115], 0, v[120:121]
	s_waitcnt lgkmcnt(0)
	v_add_f32_e32 v116, v112, v113
	v_mov_b32_e32 v117, v116
	s_nop 1
	v_permlane32_swap_b32_e32 v116, v117
	v_or_b32_e32 v112, 32, v152
	v_ashrrev_i32_e32 v113, 31, v112
	s_waitcnt lgkmcnt(0)
	v_add_f32_e32 v116, v116, v117
	v_fmamk_f32 v116, v116, 0x3a800000, v162
	v_mul_f32_e32 v117, 0x4b800000, v116
	v_cmp_gt_f32_e32 vcc, s52, v116
	s_nop 1
	v_cndmask_b32_e32 v116, v116, v117, vcc
	v_rsq_f32_e32 v118, v116
	v_lshlrev_b64 v[116:117], 6, v[112:113]
	v_lshl_add_u64 v[116:117], v[140:141], 0, v[116:117]
	v_mul_f32_e32 v113, 0x45800000, v118
	v_cndmask_b32_e32 v113, v118, v113, vcc
	v_mul_f32_e32 v119, 0xbfb8aa3b, v113
	v_mul_f32_e32 v100, v100, v119
	v_mul_f32_e32 v101, v101, v119
	v_mul_f32_e32 v102, v102, v119
	v_mul_f32_e32 v103, v103, v119
	v_mul_f32_e32 v96, v96, v119
	v_mul_f32_e32 v97, v97, v119
	v_mul_f32_e32 v98, v98, v119
	v_mul_f32_e32 v99, v99, v119
	v_exp_f32_e32 v100, v100
	v_exp_f32_e32 v101, v101
	v_exp_f32_e32 v102, v102
	v_exp_f32_e32 v103, v103
	v_exp_f32_e32 v96, v96
	v_exp_f32_e32 v97, v97
	v_exp_f32_e32 v98, v98
	v_exp_f32_e32 v99, v99
	v_mul_f32_e32 v118, v113, v113
	v_add_f32_e32 v100, 1.0, v100
	v_add_f32_e32 v101, 1.0, v101
	v_add_f32_e32 v102, 1.0, v102
	v_add_f32_e32 v103, 1.0, v103
	v_add_f32_e32 v113, 1.0, v96
	v_add_f32_e32 v119, 1.0, v97
	v_add_f32_e32 v124, 1.0, v98
	v_add_f32_e32 v125, 1.0, v99
	v_rcp_f32_e32 v96, v100
	v_rcp_f32_e32 v97, v101
	v_rcp_f32_e32 v98, v102
	v_rcp_f32_e32 v99, v103
	v_rcp_f32_e32 v100, v113
	v_rcp_f32_e32 v101, v119
	v_rcp_f32_e32 v102, v124
	v_rcp_f32_e32 v103, v125
	v_pk_mul_f32 v[96:97], v[118:119], v[96:97] op_sel_hi:[0,1]
	v_pk_mul_f32 v[98:99], v[118:119], v[98:99] op_sel_hi:[0,1]
	v_pk_mul_f32 v[100:101], v[118:119], v[100:101] op_sel_hi:[0,1]
	v_pk_mul_f32 v[102:103], v[118:119], v[102:103] op_sel_hi:[0,1]
	v_pk_mul_f32 v[96:97], v[108:109], v[96:97]
	v_pk_mul_f32 v[98:99], v[110:111], v[98:99]
	v_pk_mul_f32 v[100:101], v[104:105], v[100:101]
	v_pk_mul_f32 v[102:103], v[106:107], v[102:103]
	v_cvt_pk_bf16_f32 v96, v96, v97
	v_cvt_pk_bf16_f32 v97, v98, v99
	v_cvt_pk_bf16_f32 v98, v100, v101
	v_cvt_pk_bf16_f32 v99, v102, v103
	global_store_dwordx4 v[114:115], v[96:99], off
	s_nop 1
	v_mov_b32_e32 v96, v192
	v_mov_b32_e32 v97, v193
	v_mov_b32_e32 v98, v194
	v_mov_b32_e32 v99, v195
	v_mov_b32_e32 v100, v97
	v_mov_b32_e32 v101, v98
	v_mov_b32_e32 v97, v99
	v_pk_add_f32 v[96:97], v[100:101], v[96:97]
	v_mad_i64_i32 v[98:99], s[0:1], v112, s49, v[150:151]
	v_add_f32_e32 v96, v96, v97
	v_mov_b32_e32 v97, v96
	s_nop 1
	v_permlane16_swap_b32_e32 v96, v97
	v_lshl_add_u64 v[98:99], v[98:99], 0, v[120:121]
	s_waitcnt lgkmcnt(0)
	v_add_f32_e32 v100, v96, v97
	v_mov_b32_e32 v101, v100
	s_nop 1
	v_permlane32_swap_b32_e32 v100, v101
	v_or_b32_e32 v96, 48, v152
	v_ashrrev_i32_e32 v97, 31, v96
	s_waitcnt lgkmcnt(0)
	v_add_f32_e32 v100, v100, v101
	v_fmamk_f32 v100, v100, 0x3a800000, v162
	v_mul_f32_e32 v101, 0x4b800000, v100
	v_cmp_gt_f32_e32 vcc, s52, v100
	s_nop 1
	v_cndmask_b32_e32 v100, v100, v101, vcc
	v_rsq_f32_e32 v102, v100
	v_lshlrev_b64 v[100:101], 6, v[96:97]
	v_lshl_add_u64 v[100:101], v[140:141], 0, v[100:101]
	v_mul_f32_e32 v97, 0x45800000, v102
	v_cndmask_b32_e32 v97, v102, v97, vcc
	v_mul_f32_e32 v103, 0xbfb8aa3b, v97
	v_mul_f32_e32 v84, v84, v103
	v_mul_f32_e32 v85, v85, v103
	v_mul_f32_e32 v86, v86, v103
	v_mul_f32_e32 v87, v87, v103
	v_mul_f32_e32 v80, v80, v103
	v_mul_f32_e32 v81, v81, v103
	v_mul_f32_e32 v82, v82, v103
	v_mul_f32_e32 v83, v83, v103
	v_exp_f32_e32 v84, v84
	v_exp_f32_e32 v85, v85
	v_exp_f32_e32 v86, v86
	v_exp_f32_e32 v87, v87
	v_exp_f32_e32 v80, v80
	v_exp_f32_e32 v81, v81
	v_exp_f32_e32 v82, v82
	v_exp_f32_e32 v83, v83
	v_mul_f32_e32 v102, v97, v97
	v_add_f32_e32 v84, 1.0, v84
	v_add_f32_e32 v85, 1.0, v85
	v_add_f32_e32 v86, 1.0, v86
	v_add_f32_e32 v87, 1.0, v87
	v_add_f32_e32 v97, 1.0, v80
	v_add_f32_e32 v103, 1.0, v81
	v_add_f32_e32 v104, 1.0, v82
	v_add_f32_e32 v105, 1.0, v83
	v_rcp_f32_e32 v80, v84
	v_rcp_f32_e32 v81, v85
	v_rcp_f32_e32 v82, v86
	v_rcp_f32_e32 v83, v87
	v_rcp_f32_e32 v84, v97
	v_rcp_f32_e32 v85, v103
	v_rcp_f32_e32 v86, v104
	v_rcp_f32_e32 v87, v105
	v_pk_mul_f32 v[80:81], v[102:103], v[80:81] op_sel_hi:[0,1]
	v_pk_mul_f32 v[82:83], v[102:103], v[82:83] op_sel_hi:[0,1]
	v_pk_mul_f32 v[84:85], v[102:103], v[84:85] op_sel_hi:[0,1]
	v_pk_mul_f32 v[86:87], v[102:103], v[86:87] op_sel_hi:[0,1]
	v_pk_mul_f32 v[80:81], v[92:93], v[80:81]
	v_pk_mul_f32 v[82:83], v[94:95], v[82:83]
	v_pk_mul_f32 v[84:85], v[88:89], v[84:85]
	v_pk_mul_f32 v[86:87], v[90:91], v[86:87]
	v_cvt_pk_bf16_f32 v80, v80, v81
	v_cvt_pk_bf16_f32 v81, v82, v83
	v_cvt_pk_bf16_f32 v82, v84, v85
	v_cvt_pk_bf16_f32 v83, v86, v87
	global_store_dwordx4 v[98:99], v[80:83], off
	s_nop 1
	v_mov_b32_e32 v80, v196
	v_mov_b32_e32 v81, v197
	v_mov_b32_e32 v82, v198
	v_mov_b32_e32 v83, v199
	v_mov_b32_e32 v84, v81
	v_mov_b32_e32 v85, v82
	v_mov_b32_e32 v81, v83
	v_pk_add_f32 v[80:81], v[84:85], v[80:81]
	v_mad_i64_i32 v[82:83], s[0:1], v96, s49, v[150:151]
	v_add_f32_e32 v80, v80, v81
	v_mov_b32_e32 v81, v80
	s_nop 1
	v_permlane16_swap_b32_e32 v80, v81
	v_lshl_add_u64 v[82:83], v[82:83], 0, v[120:121]
	s_waitcnt lgkmcnt(0)
	v_add_f32_e32 v84, v80, v81
	v_mov_b32_e32 v85, v84
	s_nop 1
	v_permlane32_swap_b32_e32 v84, v85
	v_add_u32_e32 v80, 0x80, v152
	v_ashrrev_i32_e32 v81, 31, v80
	s_waitcnt lgkmcnt(0)
	v_add_f32_e32 v84, v84, v85
	v_fmamk_f32 v84, v84, 0x3a800000, v162
	v_mul_f32_e32 v85, 0x4b800000, v84
	v_cmp_gt_f32_e32 vcc, s52, v84
	s_nop 1
	v_cndmask_b32_e32 v84, v84, v85, vcc
	v_rsq_f32_e32 v86, v84
	v_lshlrev_b64 v[84:85], 6, v[80:81]
	v_lshl_add_u64 v[84:85], v[140:141], 0, v[84:85]
	v_mul_f32_e32 v81, 0x45800000, v86
	v_cndmask_b32_e32 v81, v86, v81, vcc
	v_mul_f32_e32 v87, 0xbfb8aa3b, v81
	v_mul_f32_e32 v68, v68, v87
	v_mul_f32_e32 v69, v69, v87
	v_mul_f32_e32 v70, v70, v87
	v_mul_f32_e32 v71, v71, v87
	v_mul_f32_e32 v64, v64, v87
	v_mul_f32_e32 v65, v65, v87
	v_mul_f32_e32 v66, v66, v87
	v_mul_f32_e32 v67, v67, v87
	v_exp_f32_e32 v68, v68
	v_exp_f32_e32 v69, v69
	v_exp_f32_e32 v70, v70
	v_exp_f32_e32 v71, v71
	v_exp_f32_e32 v64, v64
	v_exp_f32_e32 v65, v65
	v_exp_f32_e32 v66, v66
	v_exp_f32_e32 v67, v67
	v_mul_f32_e32 v86, v81, v81
	v_add_f32_e32 v68, 1.0, v68
	v_add_f32_e32 v69, 1.0, v69
	v_add_f32_e32 v70, 1.0, v70
	v_add_f32_e32 v71, 1.0, v71
	v_add_f32_e32 v81, 1.0, v64
	v_add_f32_e32 v87, 1.0, v65
	v_add_f32_e32 v88, 1.0, v66
	v_add_f32_e32 v89, 1.0, v67
	v_rcp_f32_e32 v64, v68
	v_rcp_f32_e32 v65, v69
	v_rcp_f32_e32 v66, v70
	v_rcp_f32_e32 v67, v71
	v_rcp_f32_e32 v68, v81
	v_rcp_f32_e32 v69, v87
	v_rcp_f32_e32 v70, v88
	v_rcp_f32_e32 v71, v89
	v_pk_mul_f32 v[64:65], v[86:87], v[64:65] op_sel_hi:[0,1]
	v_pk_mul_f32 v[66:67], v[86:87], v[66:67] op_sel_hi:[0,1]
	v_pk_mul_f32 v[68:69], v[86:87], v[68:69] op_sel_hi:[0,1]
	v_pk_mul_f32 v[70:71], v[86:87], v[70:71] op_sel_hi:[0,1]
	v_pk_mul_f32 v[64:65], v[76:77], v[64:65]
	v_pk_mul_f32 v[66:67], v[78:79], v[66:67]
	v_pk_mul_f32 v[68:69], v[72:73], v[68:69]
	v_pk_mul_f32 v[70:71], v[74:75], v[70:71]
	v_cvt_pk_bf16_f32 v64, v64, v65
	v_cvt_pk_bf16_f32 v65, v66, v67
	v_cvt_pk_bf16_f32 v66, v68, v69
	v_cvt_pk_bf16_f32 v67, v70, v71
	global_store_dwordx4 v[82:83], v[64:67], off
	s_nop 1
	v_mov_b32_e32 v64, v200
	v_mov_b32_e32 v65, v201
	v_mov_b32_e32 v66, v202
	v_mov_b32_e32 v67, v203
	v_mov_b32_e32 v68, v65
	v_mov_b32_e32 v69, v66
	v_mov_b32_e32 v65, v67
	v_pk_add_f32 v[64:65], v[68:69], v[64:65]
	v_mad_i64_i32 v[66:67], s[0:1], v80, s49, v[150:151]
	v_add_f32_e32 v64, v64, v65
	v_mov_b32_e32 v65, v64
	s_nop 1
	v_permlane16_swap_b32_e32 v64, v65
	v_lshl_add_u64 v[66:67], v[66:67], 0, v[120:121]
	s_waitcnt lgkmcnt(0)
	v_add_f32_e32 v68, v64, v65
	v_mov_b32_e32 v69, v68
	s_nop 1
	v_permlane32_swap_b32_e32 v68, v69
	v_add_u32_e32 v64, 0x90, v152
	v_ashrrev_i32_e32 v65, 31, v64
	s_waitcnt lgkmcnt(0)
	v_add_f32_e32 v68, v68, v69
	v_fmamk_f32 v68, v68, 0x3a800000, v162
	v_mul_f32_e32 v69, 0x4b800000, v68
	v_cmp_gt_f32_e32 vcc, s52, v68
	s_nop 1
	v_cndmask_b32_e32 v68, v68, v69, vcc
	v_rsq_f32_e32 v70, v68
	v_lshlrev_b64 v[68:69], 6, v[64:65]
	v_lshl_add_u64 v[68:69], v[140:141], 0, v[68:69]
	v_mul_f32_e32 v65, 0x45800000, v70
	v_cndmask_b32_e32 v65, v70, v65, vcc
	v_mul_f32_e32 v71, 0xbfb8aa3b, v65
	v_mul_f32_e32 v52, v52, v71
	v_mul_f32_e32 v53, v53, v71
	v_mul_f32_e32 v54, v54, v71
	v_mul_f32_e32 v55, v55, v71
	v_mul_f32_e32 v48, v48, v71
	v_mul_f32_e32 v49, v49, v71
	v_mul_f32_e32 v50, v50, v71
	v_mul_f32_e32 v51, v51, v71
	v_exp_f32_e32 v52, v52
	v_exp_f32_e32 v53, v53
	v_exp_f32_e32 v54, v54
	v_exp_f32_e32 v55, v55
	v_exp_f32_e32 v48, v48
	v_exp_f32_e32 v49, v49
	v_exp_f32_e32 v50, v50
	v_exp_f32_e32 v51, v51
	v_mul_f32_e32 v70, v65, v65
	v_add_f32_e32 v52, 1.0, v52
	v_add_f32_e32 v53, 1.0, v53
	v_add_f32_e32 v54, 1.0, v54
	v_add_f32_e32 v55, 1.0, v55
	v_add_f32_e32 v65, 1.0, v48
	v_add_f32_e32 v71, 1.0, v49
	v_add_f32_e32 v72, 1.0, v50
	v_add_f32_e32 v73, 1.0, v51
	v_rcp_f32_e32 v48, v52
	v_rcp_f32_e32 v49, v53
	v_rcp_f32_e32 v50, v54
	v_rcp_f32_e32 v51, v55
	v_rcp_f32_e32 v52, v65
	v_rcp_f32_e32 v53, v71
	v_rcp_f32_e32 v54, v72
	v_rcp_f32_e32 v55, v73
	v_pk_mul_f32 v[48:49], v[70:71], v[48:49] op_sel_hi:[0,1]
	v_pk_mul_f32 v[50:51], v[70:71], v[50:51] op_sel_hi:[0,1]
	v_pk_mul_f32 v[52:53], v[70:71], v[52:53] op_sel_hi:[0,1]
	v_pk_mul_f32 v[54:55], v[70:71], v[54:55] op_sel_hi:[0,1]
	v_pk_mul_f32 v[48:49], v[60:61], v[48:49]
	v_pk_mul_f32 v[50:51], v[62:63], v[50:51]
	v_pk_mul_f32 v[52:53], v[56:57], v[52:53]
	v_pk_mul_f32 v[54:55], v[58:59], v[54:55]
	v_cvt_pk_bf16_f32 v48, v48, v49
	v_cvt_pk_bf16_f32 v49, v50, v51
	v_cvt_pk_bf16_f32 v50, v52, v53
	v_cvt_pk_bf16_f32 v51, v54, v55
	global_store_dwordx4 v[66:67], v[48:51], off
	s_nop 1
	v_mov_b32_e32 v48, v204
	v_mov_b32_e32 v49, v205
	v_mov_b32_e32 v50, v206
	v_mov_b32_e32 v51, v207
	v_mov_b32_e32 v52, v49
	v_mov_b32_e32 v53, v50
	v_mov_b32_e32 v49, v51
	v_pk_add_f32 v[48:49], v[52:53], v[48:49]
	v_mad_i64_i32 v[50:51], s[0:1], v64, s49, v[150:151]
	v_add_f32_e32 v48, v48, v49
	v_mov_b32_e32 v49, v48
	s_nop 1
	v_permlane16_swap_b32_e32 v48, v49
	v_lshl_add_u64 v[50:51], v[50:51], 0, v[120:121]
	s_waitcnt lgkmcnt(0)
	v_add_f32_e32 v52, v48, v49
	v_mov_b32_e32 v53, v52
	s_nop 1
	v_permlane32_swap_b32_e32 v52, v53
	v_add_u32_e32 v48, 0xa0, v152
	v_ashrrev_i32_e32 v49, 31, v48
	s_waitcnt lgkmcnt(0)
	v_add_f32_e32 v52, v52, v53
	v_fmamk_f32 v52, v52, 0x3a800000, v162
	v_mul_f32_e32 v53, 0x4b800000, v52
	v_cmp_gt_f32_e32 vcc, s52, v52
	s_nop 1
	v_cndmask_b32_e32 v52, v52, v53, vcc
	v_rsq_f32_e32 v54, v52
	v_lshlrev_b64 v[52:53], 6, v[48:49]
	v_lshl_add_u64 v[52:53], v[140:141], 0, v[52:53]
	v_mul_f32_e32 v49, 0x45800000, v54
	v_cndmask_b32_e32 v49, v54, v49, vcc
	v_mul_f32_e32 v55, 0xbfb8aa3b, v49
	v_mul_f32_e32 v36, v36, v55
	v_mul_f32_e32 v37, v37, v55
	v_mul_f32_e32 v38, v38, v55
	v_mul_f32_e32 v39, v39, v55
	v_mul_f32_e32 v32, v32, v55
	v_mul_f32_e32 v33, v33, v55
	v_mul_f32_e32 v34, v34, v55
	v_mul_f32_e32 v35, v35, v55
	v_exp_f32_e32 v36, v36
	v_exp_f32_e32 v37, v37
	v_exp_f32_e32 v38, v38
	v_exp_f32_e32 v39, v39
	v_exp_f32_e32 v32, v32
	v_exp_f32_e32 v33, v33
	v_exp_f32_e32 v34, v34
	v_exp_f32_e32 v35, v35
	v_mul_f32_e32 v54, v49, v49
	v_add_f32_e32 v36, 1.0, v36
	v_add_f32_e32 v37, 1.0, v37
	v_add_f32_e32 v38, 1.0, v38
	v_add_f32_e32 v39, 1.0, v39
	v_add_f32_e32 v49, 1.0, v32
	v_add_f32_e32 v55, 1.0, v33
	v_add_f32_e32 v56, 1.0, v34
	v_add_f32_e32 v57, 1.0, v35
	v_rcp_f32_e32 v32, v36
	v_rcp_f32_e32 v33, v37
	v_rcp_f32_e32 v34, v38
	v_rcp_f32_e32 v35, v39
	v_rcp_f32_e32 v36, v49
	v_rcp_f32_e32 v37, v55
	v_rcp_f32_e32 v38, v56
	v_rcp_f32_e32 v39, v57
	v_pk_mul_f32 v[32:33], v[54:55], v[32:33] op_sel_hi:[0,1]
	v_pk_mul_f32 v[34:35], v[54:55], v[34:35] op_sel_hi:[0,1]
	v_pk_mul_f32 v[36:37], v[54:55], v[36:37] op_sel_hi:[0,1]
	v_pk_mul_f32 v[38:39], v[54:55], v[38:39] op_sel_hi:[0,1]
	v_pk_mul_f32 v[32:33], v[44:45], v[32:33]
	v_pk_mul_f32 v[34:35], v[46:47], v[34:35]
	v_pk_mul_f32 v[36:37], v[40:41], v[36:37]
	v_pk_mul_f32 v[38:39], v[42:43], v[38:39]
	v_cvt_pk_bf16_f32 v32, v32, v33
	v_cvt_pk_bf16_f32 v33, v34, v35
	v_cvt_pk_bf16_f32 v34, v36, v37
	v_cvt_pk_bf16_f32 v35, v38, v39
	global_store_dwordx4 v[50:51], v[32:35], off
	s_nop 1
	v_mov_b32_e32 v32, v208
	v_mov_b32_e32 v33, v209
	v_mov_b32_e32 v34, v210
	v_mov_b32_e32 v35, v211
	v_mov_b32_e32 v36, v33
	v_mov_b32_e32 v37, v34
	v_mov_b32_e32 v33, v35
	v_pk_add_f32 v[32:33], v[36:37], v[32:33]
	v_mad_i64_i32 v[34:35], s[0:1], v48, s49, v[150:151]
	v_add_f32_e32 v32, v32, v33
	v_mov_b32_e32 v33, v32
	s_nop 1
	v_permlane16_swap_b32_e32 v32, v33
	v_lshl_add_u64 v[34:35], v[34:35], 0, v[120:121]
	s_waitcnt lgkmcnt(0)
	v_add_f32_e32 v36, v32, v33
	v_mov_b32_e32 v37, v36
	s_nop 1
	v_permlane32_swap_b32_e32 v36, v37
	v_add_u32_e32 v32, 0xb0, v152
	v_ashrrev_i32_e32 v33, 31, v32
	s_waitcnt lgkmcnt(0)
	v_add_f32_e32 v36, v36, v37
	v_fmamk_f32 v36, v36, 0x3a800000, v162
	v_mul_f32_e32 v37, 0x4b800000, v36
	v_cmp_gt_f32_e32 vcc, s52, v36
	s_nop 1
	v_cndmask_b32_e32 v36, v36, v37, vcc
	v_rsq_f32_e32 v38, v36
	v_lshlrev_b64 v[36:37], 6, v[32:33]
	v_lshl_add_u64 v[36:37], v[140:141], 0, v[36:37]
	v_mul_f32_e32 v33, 0x45800000, v38
	v_cndmask_b32_e32 v33, v38, v33, vcc
	v_mul_f32_e32 v39, 0xbfb8aa3b, v33
	v_mul_f32_e32 v20, v20, v39
	v_mul_f32_e32 v21, v21, v39
	v_mul_f32_e32 v22, v22, v39
	v_mul_f32_e32 v23, v23, v39
	v_mul_f32_e32 v16, v16, v39
	v_mul_f32_e32 v17, v17, v39
	v_mul_f32_e32 v18, v18, v39
	v_mul_f32_e32 v19, v19, v39
	v_exp_f32_e32 v20, v20
	v_exp_f32_e32 v21, v21
	v_exp_f32_e32 v22, v22
	v_exp_f32_e32 v23, v23
	v_exp_f32_e32 v16, v16
	v_exp_f32_e32 v17, v17
	v_exp_f32_e32 v18, v18
	v_exp_f32_e32 v19, v19
	v_mul_f32_e32 v38, v33, v33
	v_add_f32_e32 v20, 1.0, v20
	v_add_f32_e32 v21, 1.0, v21
	v_add_f32_e32 v22, 1.0, v22
	v_add_f32_e32 v23, 1.0, v23
	v_add_f32_e32 v33, 1.0, v16
	v_add_f32_e32 v39, 1.0, v17
	v_add_f32_e32 v40, 1.0, v18
	v_add_f32_e32 v41, 1.0, v19
	v_rcp_f32_e32 v16, v20
	v_rcp_f32_e32 v17, v21
	v_rcp_f32_e32 v18, v22
	v_rcp_f32_e32 v19, v23
	v_rcp_f32_e32 v20, v33
	v_rcp_f32_e32 v21, v39
	v_rcp_f32_e32 v22, v40
	v_rcp_f32_e32 v23, v41
	v_pk_mul_f32 v[16:17], v[38:39], v[16:17] op_sel_hi:[0,1]
	v_pk_mul_f32 v[18:19], v[38:39], v[18:19] op_sel_hi:[0,1]
	v_pk_mul_f32 v[20:21], v[38:39], v[20:21] op_sel_hi:[0,1]
	v_pk_mul_f32 v[22:23], v[38:39], v[22:23] op_sel_hi:[0,1]
	v_pk_mul_f32 v[16:17], v[28:29], v[16:17]
	v_pk_mul_f32 v[18:19], v[30:31], v[18:19]
	v_pk_mul_f32 v[20:21], v[24:25], v[20:21]
	v_pk_mul_f32 v[22:23], v[26:27], v[22:23]
	v_cvt_pk_bf16_f32 v16, v16, v17
	v_cvt_pk_bf16_f32 v17, v18, v19
	v_cvt_pk_bf16_f32 v18, v20, v21
	v_cvt_pk_bf16_f32 v19, v22, v23
	global_store_dwordx4 v[34:35], v[16:19], off
	s_andn2_b64 vcc, exec, s[4:5]
	s_nop 1
	v_mov_b32_e32 v16, v212
	v_mov_b32_e32 v17, v213
	v_mov_b32_e32 v18, v214
	v_mov_b32_e32 v19, v215
	v_mov_b32_e32 v20, v17
	v_mov_b32_e32 v21, v18
	v_mov_b32_e32 v17, v19
	v_pk_add_f32 v[16:17], v[20:21], v[16:17]
	s_nop 0
	v_add_f32_e32 v16, v16, v17
	v_mov_b32_e32 v17, v16
	s_nop 1
	v_permlane16_swap_b32_e32 v16, v17
	s_waitcnt lgkmcnt(0)
	v_add_f32_e32 v16, v16, v17
	v_mov_b32_e32 v17, v16
	s_nop 1
	v_permlane32_swap_b32_e32 v16, v17
	s_waitcnt lgkmcnt(0)
	v_add_f32_e32 v16, v16, v17
	v_fmamk_f32 v16, v16, 0x3a800000, v162
	v_mul_f32_e32 v17, 0x4b800000, v16
	v_cmp_gt_f32_e64 s[0:1], s52, v16
	s_nop 1
	v_cndmask_b32_e64 v16, v16, v17, s[0:1]
	v_rsq_f32_e32 v18, v16
	v_mad_i64_i32 v[16:17], s[24:25], v32, s49, v[150:151]
	v_lshl_add_u64 v[16:17], v[16:17], 0, v[120:121]
	v_mul_f32_e32 v19, 0x45800000, v18
	v_cndmask_b32_e64 v18, v18, v19, s[0:1]
	v_mul_f32_e32 v19, 0xbfb8aa3b, v18
	v_mul_f32_e32 v4, v4, v19
	v_mul_f32_e32 v5, v5, v19
	v_mul_f32_e32 v6, v6, v19
	v_mul_f32_e32 v7, v7, v19
	v_mul_f32_e32 v0, v0, v19
	v_mul_f32_e32 v1, v1, v19
	v_mul_f32_e32 v2, v2, v19
	v_mul_f32_e32 v3, v3, v19
	v_exp_f32_e32 v4, v4
	v_exp_f32_e32 v5, v5
	v_exp_f32_e32 v6, v6
	v_exp_f32_e32 v7, v7
	v_exp_f32_e32 v0, v0
	v_exp_f32_e32 v1, v1
	v_exp_f32_e32 v2, v2
	v_exp_f32_e32 v3, v3
	v_add_f32_e32 v4, 1.0, v4
	v_add_f32_e32 v5, 1.0, v5
	v_add_f32_e32 v6, 1.0, v6
	v_add_f32_e32 v7, 1.0, v7
	v_add_f32_e32 v19, 1.0, v0
	v_add_f32_e32 v20, 1.0, v1
	v_add_f32_e32 v21, 1.0, v2
	v_add_f32_e32 v22, 1.0, v3
	v_rcp_f32_e32 v0, v4
	v_rcp_f32_e32 v1, v5
	v_rcp_f32_e32 v2, v6
	v_rcp_f32_e32 v3, v7
	v_rcp_f32_e32 v4, v19
	v_rcp_f32_e32 v5, v20
	v_rcp_f32_e32 v6, v21
	v_rcp_f32_e32 v7, v22
	v_mul_f32_e32 v18, v18, v18
	v_pk_mul_f32 v[0:1], v[18:19], v[0:1] op_sel_hi:[0,1]
	v_pk_mul_f32 v[2:3], v[18:19], v[2:3] op_sel_hi:[0,1]
	v_pk_mul_f32 v[4:5], v[18:19], v[4:5] op_sel_hi:[0,1]
	v_pk_mul_f32 v[6:7], v[18:19], v[6:7] op_sel_hi:[0,1]
	v_pk_mul_f32 v[0:1], v[12:13], v[0:1]
	v_pk_mul_f32 v[2:3], v[14:15], v[2:3]
	v_pk_mul_f32 v[4:5], v[8:9], v[4:5]
	v_pk_mul_f32 v[6:7], v[10:11], v[6:7]
	v_cvt_pk_bf16_f32 v0, v0, v1
	v_cvt_pk_bf16_f32 v1, v2, v3
	v_cvt_pk_bf16_f32 v2, v4, v5
	v_cvt_pk_bf16_f32 v3, v6, v7
	s_mov_b64 s[0:1], -1
	global_store_dwordx4 v[16:17], v[0:3], off
	s_cbranch_vccnz .LBB0_620
	s_andn2_b64 vcc, exec, s[8:9]
	s_cbranch_vccnz .LBB0_619
	s_barrier
	s_branch .LBB0_619

.LBB0_712:
	v_lshl_add_u32 v150, s53, 8, v152
	v_ashrrev_i32_e32 v151, 31, v150
	v_lshl_or_b32 v148, s10, 8, v154
	v_lshlrev_b64 v[160:161], 11, v[150:151]
	v_ashrrev_i32_e32 v149, 31, v148
	v_lshl_add_u64 v[160:161], s[14:15], 0, v[160:161]
	v_lshl_add_u64 v[170:171], v[148:149], 1, v[160:161]
	global_load_dwordx4 v[162:165], v[170:171], off
	global_load_dwordx4 v[166:169], v[170:171], off offset:256
	s_mov_b64 s[100:101], 0x8000
	v_lshl_add_u64 v[232:233], v[170:171], 0, s[100:101]
	global_load_dwordx4 v[184:187], v[232:233], off
	global_load_dwordx4 v[188:191], v[232:233], off offset:256
	s_mov_b64 s[100:101], 0x10000
	v_lshl_add_u64 v[232:233], v[170:171], 0, s[100:101]
	global_load_dwordx4 v[192:195], v[232:233], off
	global_load_dwordx4 v[196:199], v[232:233], off offset:256
	s_mov_b64 s[100:101], 0x18000
	v_lshl_add_u64 v[232:233], v[170:171], 0, s[100:101]
	global_load_dwordx4 v[200:203], v[232:233], off
	global_load_dwordx4 v[204:207], v[232:233], off offset:256
	s_mov_b64 s[100:101], 0x40000
	v_lshl_add_u64 v[232:233], v[170:171], 0, s[100:101]
	global_load_dwordx4 v[208:211], v[232:233], off
	global_load_dwordx4 v[212:215], v[232:233], off offset:256
	s_mov_b64 s[100:101], 0x48000
	v_lshl_add_u64 v[232:233], v[170:171], 0, s[100:101]
	global_load_dwordx4 v[216:219], v[232:233], off
	global_load_dwordx4 v[220:223], v[232:233], off offset:256
	s_mov_b64 s[100:101], 0x50000
	v_lshl_add_u64 v[232:233], v[170:171], 0, s[100:101]
	global_load_dwordx4 v[224:227], v[232:233], off
	global_load_dwordx4 v[228:231], v[232:233], off offset:256
	s_mov_b64 s[100:101], 0x58000
	v_lshl_add_u64 v[232:233], v[170:171], 0, s[100:101]
	global_load_dwordx4 v[238:241], v[232:233], off
	global_load_dwordx4 v[242:245], v[232:233], off offset:256
	v_and_b32_e32 v161, 64, v159
	v_xor_b32_e32 v160, 16, v159
	v_add_u32_e32 v161, 64, v161
	v_xor_b32_e32 v172, 32, v159
	v_cmp_lt_i32_e32 vcc, v160, v161
	s_lshl_b32 s24, s10, 2
	s_ashr_i32 s25, s24, 31
	v_cndmask_b32_e32 v160, v159, v160, vcc
	v_cmp_lt_i32_e32 vcc, v172, v161
	v_lshlrev_b32_e32 v161, 2, v160
	s_waitcnt vmcnt(0)
	v_and_b32_e32 v173, 0xffff0000, v162
	v_cndmask_b32_e32 v172, v159, v172, vcc
	v_lshlrev_b32_e32 v160, 2, v172
	v_lshlrev_b32_e32 v172, 16, v162
	v_lshlrev_b32_e32 v162, 16, v163
	v_and_b32_e32 v163, 0xffff0000, v163
	v_lshlrev_b32_e32 v174, 16, v164
	v_and_b32_e32 v175, 0xffff0000, v164
	v_lshlrev_b32_e32 v164, 16, v165
	v_and_b32_e32 v165, 0xffff0000, v165
	v_lshlrev_b32_e32 v176, 16, v166
	v_and_b32_e32 v177, 0xffff0000, v166
	v_lshlrev_b32_e32 v166, 16, v167
	v_and_b32_e32 v167, 0xffff0000, v167
	v_lshlrev_b32_e32 v178, 16, v168
	v_and_b32_e32 v179, 0xffff0000, v168
	v_lshlrev_b32_e32 v168, 16, v169
	v_and_b32_e32 v169, 0xffff0000, v169
	v_pk_add_f32 v[124:125], v[124:125], v[172:173]
	v_pk_add_f32 v[126:127], v[126:127], v[162:163]
	v_pk_add_f32 v[120:121], v[120:121], v[174:175]
	v_pk_add_f32 v[122:123], v[122:123], v[164:165]
	v_pk_add_f32 v[116:117], v[116:117], v[176:177]
	v_pk_add_f32 v[118:119], v[118:119], v[166:167]
	v_pk_add_f32 v[162:163], v[112:113], v[178:179]
	v_pk_add_f32 v[164:165], v[114:115], v[168:169]
	v_cvt_pk_bf16_f32 v112, v124, v125
	v_cvt_pk_bf16_f32 v113, v126, v127
	v_pk_mul_f32 v[114:115], v[124:125], v[124:125]
	v_pk_mul_f32 v[124:125], v[126:127], v[126:127]
	v_pk_mul_f32 v[126:127], v[120:121], v[120:121]
	v_pk_mul_f32 v[166:167], v[122:123], v[122:123]
	v_pk_mul_f32 v[168:169], v[116:117], v[116:117]
	v_pk_mul_f32 v[172:173], v[118:119], v[118:119]
	v_pk_mul_f32 v[174:175], v[162:163], v[162:163]
	v_pk_mul_f32 v[176:177], v[164:165], v[164:165]
	v_add_f32_e32 v174, v174, v175
	v_add_f32_e32 v176, v176, v177
	v_add_f32_e32 v172, v172, v173
	v_add_f32_e32 v168, v168, v169
	v_add_f32_e32 v166, v166, v167
	v_add_f32_e32 v126, v126, v127
	v_add_f32_e32 v124, v124, v125
	v_add_f32_e32 v114, v114, v115
	v_add_f32_e32 v115, v174, v176
	v_add_f32_e32 v125, v168, v172
	v_add_f32_e32 v126, v126, v166
	v_add_f32_e32 v114, v114, v124
	v_add_f32_e32 v115, v125, v115
	v_add_f32_e32 v114, v114, v126
	v_add_f32_e32 v124, v114, v115
	v_mov_b32_e32 v125, v124
	s_nop 1
	v_permlane16_swap_b32_e32 v124, v125
	v_cvt_pk_bf16_f32 v114, v120, v121
	v_cvt_pk_bf16_f32 v115, v122, v123
	global_store_dwordx4 v[170:171], v[112:115], off
	s_waitcnt lgkmcnt(0)
	s_nop 0
	v_add_f32_e32 v112, v124, v125
	v_mov_b32_e32 v113, v112
	s_nop 1
	v_permlane32_swap_b32_e32 v112, v113
	v_cvt_pk_bf16_f32 v114, v116, v117
	v_cvt_pk_bf16_f32 v115, v118, v119
	v_cvt_pk_bf16_f32 v116, v162, v163
	v_cvt_pk_bf16_f32 v117, v164, v165
	global_store_dwordx4 v[170:171], v[114:117], off offset:256
	s_and_saveexec_b64 s[26:27], s[4:5]
	s_cbranch_execz .LBB0_714
	v_lshlrev_b64 v[114:115], 6, v[150:151]
	v_lshl_add_u64 v[114:115], s[16:17], 0, v[114:115]
	v_lshl_add_u64 v[114:115], s[24:25], 2, v[114:115]
	s_lshl_b32 s10, s40, 2
	v_lshl_add_u64 v[114:115], v[114:115], 0, s[10:11]
	s_waitcnt lgkmcnt(0)
	v_add_f32_e32 v112, v112, v113
	global_store_dword v[114:115], v112, off
.LBB0_714:
	s_or_b64 exec, exec, s[26:27]
	v_or_b32_e32 v112, 16, v150
	s_waitcnt lgkmcnt(0)
	v_ashrrev_i32_e32 v113, 31, v112
	v_lshlrev_b64 v[114:115], 11, v[112:113]
	v_lshl_add_u64 v[114:115], s[14:15], 0, v[114:115]
	v_lshl_add_u64 v[122:123], v[148:149], 1, v[114:115]
	s_nop 1
	v_mov_b32_e32 v114, v184
	v_mov_b32_e32 v115, v185
	v_mov_b32_e32 v116, v186
	v_mov_b32_e32 v117, v187
	v_mov_b32_e32 v118, v188
	v_mov_b32_e32 v119, v189
	v_mov_b32_e32 v120, v190
	v_mov_b32_e32 v121, v191
	v_lshlrev_b32_e32 v124, 16, v114
	v_and_b32_e32 v125, 0xffff0000, v114
	v_lshlrev_b32_e32 v114, 16, v115
	v_and_b32_e32 v115, 0xffff0000, v115
	v_lshlrev_b32_e32 v126, 16, v116
	v_and_b32_e32 v127, 0xffff0000, v116
	v_lshlrev_b32_e32 v116, 16, v117
	v_and_b32_e32 v117, 0xffff0000, v117
	v_lshlrev_b32_e32 v162, 16, v118
	v_and_b32_e32 v163, 0xffff0000, v118
	v_lshlrev_b32_e32 v118, 16, v119
	v_and_b32_e32 v119, 0xffff0000, v119
	v_lshlrev_b32_e32 v164, 16, v120
	v_and_b32_e32 v165, 0xffff0000, v120
	v_lshlrev_b32_e32 v120, 16, v121
	v_and_b32_e32 v121, 0xffff0000, v121
	v_pk_add_f32 v[108:109], v[108:109], v[124:125]
	v_pk_add_f32 v[110:111], v[110:111], v[114:115]
	v_pk_add_f32 v[104:105], v[104:105], v[126:127]
	v_pk_add_f32 v[106:107], v[106:107], v[116:117]
	v_pk_add_f32 v[100:101], v[100:101], v[162:163]
	v_pk_add_f32 v[102:103], v[102:103], v[118:119]
	v_pk_add_f32 v[114:115], v[96:97], v[164:165]
	v_pk_add_f32 v[116:117], v[98:99], v[120:121]
	v_cvt_pk_bf16_f32 v96, v108, v109
	v_cvt_pk_bf16_f32 v97, v110, v111
	v_pk_mul_f32 v[98:99], v[108:109], v[108:109]
	v_pk_mul_f32 v[108:109], v[110:111], v[110:111]
	v_pk_mul_f32 v[110:111], v[104:105], v[104:105]
	v_pk_mul_f32 v[118:119], v[106:107], v[106:107]
	v_pk_mul_f32 v[120:121], v[100:101], v[100:101]
	v_pk_mul_f32 v[124:125], v[102:103], v[102:103]
	v_pk_mul_f32 v[126:127], v[114:115], v[114:115]
	v_pk_mul_f32 v[162:163], v[116:117], v[116:117]
	v_add_f32_e32 v126, v126, v127
	v_add_f32_e32 v151, v162, v163
	v_add_f32_e32 v124, v124, v125
	v_add_f32_e32 v120, v120, v121
	v_add_f32_e32 v118, v118, v119
	v_add_f32_e32 v110, v110, v111
	v_add_f32_e32 v108, v108, v109
	v_add_f32_e32 v98, v98, v99
	v_add_f32_e32 v99, v126, v151
	v_add_f32_e32 v109, v120, v124
	v_add_f32_e32 v110, v110, v118
	v_add_f32_e32 v98, v98, v108
	v_add_f32_e32 v99, v109, v99
	v_add_f32_e32 v98, v98, v110
	v_add_f32_e32 v108, v98, v99
	v_mov_b32_e32 v109, v108
	s_nop 1
	v_permlane16_swap_b32_e32 v108, v109
	v_cvt_pk_bf16_f32 v98, v104, v105
	v_cvt_pk_bf16_f32 v99, v106, v107
	global_store_dwordx4 v[122:123], v[96:99], off
	s_waitcnt lgkmcnt(0)
	s_nop 0
	v_add_f32_e32 v96, v108, v109
	v_mov_b32_e32 v97, v96
	s_nop 1
	v_permlane32_swap_b32_e32 v96, v97
	v_cvt_pk_bf16_f32 v98, v100, v101
	v_cvt_pk_bf16_f32 v99, v102, v103
	v_cvt_pk_bf16_f32 v100, v114, v115
	v_cvt_pk_bf16_f32 v101, v116, v117
	global_store_dwordx4 v[122:123], v[98:101], off offset:256
	s_and_saveexec_b64 s[26:27], s[4:5]
	s_cbranch_execz .LBB0_716
	v_lshlrev_b64 v[98:99], 6, v[112:113]
	v_lshl_add_u64 v[98:99], s[16:17], 0, v[98:99]
	v_lshl_add_u64 v[98:99], s[24:25], 2, v[98:99]
	s_lshl_b32 s10, s40, 2
	v_lshl_add_u64 v[98:99], v[98:99], 0, s[10:11]
	s_waitcnt lgkmcnt(0)
	v_add_f32_e32 v96, v96, v97
	global_store_dword v[98:99], v96, off
.LBB0_716:
	s_or_b64 exec, exec, s[26:27]
	v_or_b32_e32 v96, 32, v150
	s_waitcnt lgkmcnt(0)
	v_ashrrev_i32_e32 v97, 31, v96
	v_lshlrev_b64 v[98:99], 11, v[96:97]
	v_lshl_add_u64 v[98:99], s[14:15], 0, v[98:99]
	v_lshl_add_u64 v[106:107], v[148:149], 1, v[98:99]
	s_nop 1
	v_mov_b32_e32 v98, v192
	v_mov_b32_e32 v99, v193
	v_mov_b32_e32 v100, v194
	v_mov_b32_e32 v101, v195
	v_mov_b32_e32 v102, v196
	v_mov_b32_e32 v103, v197
	v_mov_b32_e32 v104, v198
	v_mov_b32_e32 v105, v199
	v_lshlrev_b32_e32 v108, 16, v98
	v_and_b32_e32 v109, 0xffff0000, v98
	v_lshlrev_b32_e32 v98, 16, v99
	v_and_b32_e32 v99, 0xffff0000, v99
	v_lshlrev_b32_e32 v110, 16, v100
	v_and_b32_e32 v111, 0xffff0000, v100
	v_lshlrev_b32_e32 v100, 16, v101
	v_and_b32_e32 v101, 0xffff0000, v101
	v_lshlrev_b32_e32 v112, 16, v102
	v_and_b32_e32 v113, 0xffff0000, v102
	v_lshlrev_b32_e32 v102, 16, v103
	v_and_b32_e32 v103, 0xffff0000, v103
	v_lshlrev_b32_e32 v114, 16, v104
	v_and_b32_e32 v115, 0xffff0000, v104
	v_lshlrev_b32_e32 v104, 16, v105
	v_and_b32_e32 v105, 0xffff0000, v105
	v_pk_add_f32 v[92:93], v[92:93], v[108:109]
	v_pk_add_f32 v[94:95], v[94:95], v[98:99]
	v_pk_add_f32 v[88:89], v[88:89], v[110:111]
	v_pk_add_f32 v[90:91], v[90:91], v[100:101]
	v_pk_add_f32 v[84:85], v[84:85], v[112:113]
	v_pk_add_f32 v[86:87], v[86:87], v[102:103]
	v_pk_add_f32 v[98:99], v[80:81], v[114:115]
	v_pk_add_f32 v[100:101], v[82:83], v[104:105]
	v_cvt_pk_bf16_f32 v80, v92, v93
	v_cvt_pk_bf16_f32 v81, v94, v95
	v_pk_mul_f32 v[82:83], v[92:93], v[92:93]
	v_pk_mul_f32 v[92:93], v[94:95], v[94:95]
	v_pk_mul_f32 v[94:95], v[88:89], v[88:89]
	v_pk_mul_f32 v[102:103], v[90:91], v[90:91]
	v_pk_mul_f32 v[104:105], v[84:85], v[84:85]
	v_pk_mul_f32 v[108:109], v[86:87], v[86:87]
	v_pk_mul_f32 v[110:111], v[98:99], v[98:99]
	v_pk_mul_f32 v[112:113], v[100:101], v[100:101]
	v_add_f32_e32 v110, v110, v111
	v_add_f32_e32 v112, v112, v113
	v_add_f32_e32 v108, v108, v109
	v_add_f32_e32 v104, v104, v105
	v_add_f32_e32 v102, v102, v103
	v_add_f32_e32 v94, v94, v95
	v_add_f32_e32 v92, v92, v93
	v_add_f32_e32 v82, v82, v83
	v_add_f32_e32 v83, v110, v112
	v_add_f32_e32 v93, v104, v108
	v_add_f32_e32 v94, v94, v102
	v_add_f32_e32 v82, v82, v92
	v_add_f32_e32 v83, v93, v83
	v_add_f32_e32 v82, v82, v94
	v_add_f32_e32 v92, v82, v83
	v_mov_b32_e32 v93, v92
	s_nop 1
	v_permlane16_swap_b32_e32 v92, v93
	v_cvt_pk_bf16_f32 v82, v88, v89
	v_cvt_pk_bf16_f32 v83, v90, v91
	global_store_dwordx4 v[106:107], v[80:83], off
	s_waitcnt lgkmcnt(0)
	s_nop 0
	v_add_f32_e32 v80, v92, v93
	v_mov_b32_e32 v81, v80
	s_nop 1
	v_permlane32_swap_b32_e32 v80, v81
	v_cvt_pk_bf16_f32 v82, v84, v85
	v_cvt_pk_bf16_f32 v83, v86, v87
	v_cvt_pk_bf16_f32 v84, v98, v99
	v_cvt_pk_bf16_f32 v85, v100, v101
	global_store_dwordx4 v[106:107], v[82:85], off offset:256
	s_and_saveexec_b64 s[26:27], s[4:5]
	s_cbranch_execz .LBB0_718
	v_lshlrev_b64 v[82:83], 6, v[96:97]
	v_lshl_add_u64 v[82:83], s[16:17], 0, v[82:83]
	v_lshl_add_u64 v[82:83], s[24:25], 2, v[82:83]
	s_lshl_b32 s10, s40, 2
	v_lshl_add_u64 v[82:83], v[82:83], 0, s[10:11]
	s_waitcnt lgkmcnt(0)
	v_add_f32_e32 v80, v80, v81
	global_store_dword v[82:83], v80, off
.LBB0_718:
	s_or_b64 exec, exec, s[26:27]
	v_or_b32_e32 v80, 48, v150
	s_waitcnt lgkmcnt(0)
	v_ashrrev_i32_e32 v81, 31, v80
	v_lshlrev_b64 v[82:83], 11, v[80:81]
	v_lshl_add_u64 v[82:83], s[14:15], 0, v[82:83]
	v_lshl_add_u64 v[90:91], v[148:149], 1, v[82:83]
	s_nop 1
	v_mov_b32_e32 v82, v200
	v_mov_b32_e32 v83, v201
	v_mov_b32_e32 v84, v202
	v_mov_b32_e32 v85, v203
	v_mov_b32_e32 v86, v204
	v_mov_b32_e32 v87, v205
	v_mov_b32_e32 v88, v206
	v_mov_b32_e32 v89, v207
	v_lshlrev_b32_e32 v92, 16, v82
	v_and_b32_e32 v93, 0xffff0000, v82
	v_lshlrev_b32_e32 v82, 16, v83
	v_and_b32_e32 v83, 0xffff0000, v83
	v_lshlrev_b32_e32 v94, 16, v84
	v_and_b32_e32 v95, 0xffff0000, v84
	v_lshlrev_b32_e32 v84, 16, v85
	v_and_b32_e32 v85, 0xffff0000, v85
	v_lshlrev_b32_e32 v96, 16, v86
	v_and_b32_e32 v97, 0xffff0000, v86
	v_lshlrev_b32_e32 v86, 16, v87
	v_and_b32_e32 v87, 0xffff0000, v87
	v_lshlrev_b32_e32 v98, 16, v88
	v_and_b32_e32 v99, 0xffff0000, v88
	v_lshlrev_b32_e32 v88, 16, v89
	v_and_b32_e32 v89, 0xffff0000, v89
	v_pk_add_f32 v[76:77], v[76:77], v[92:93]
	v_pk_add_f32 v[78:79], v[78:79], v[82:83]
	v_pk_add_f32 v[72:73], v[72:73], v[94:95]
	v_pk_add_f32 v[74:75], v[74:75], v[84:85]
	v_pk_add_f32 v[68:69], v[68:69], v[96:97]
	v_pk_add_f32 v[70:71], v[70:71], v[86:87]
	v_pk_add_f32 v[82:83], v[64:65], v[98:99]
	v_pk_add_f32 v[84:85], v[66:67], v[88:89]
	v_cvt_pk_bf16_f32 v64, v76, v77
	v_cvt_pk_bf16_f32 v65, v78, v79
	v_pk_mul_f32 v[66:67], v[76:77], v[76:77]
	v_pk_mul_f32 v[76:77], v[78:79], v[78:79]
	v_pk_mul_f32 v[78:79], v[72:73], v[72:73]
	v_pk_mul_f32 v[86:87], v[74:75], v[74:75]
	v_pk_mul_f32 v[88:89], v[68:69], v[68:69]
	v_pk_mul_f32 v[92:93], v[70:71], v[70:71]
	v_pk_mul_f32 v[94:95], v[82:83], v[82:83]
	v_pk_mul_f32 v[96:97], v[84:85], v[84:85]
	v_add_f32_e32 v94, v94, v95
	v_add_f32_e32 v96, v96, v97
	v_add_f32_e32 v92, v92, v93
	v_add_f32_e32 v88, v88, v89
	v_add_f32_e32 v86, v86, v87
	v_add_f32_e32 v78, v78, v79
	v_add_f32_e32 v76, v76, v77
	v_add_f32_e32 v66, v66, v67
	v_add_f32_e32 v67, v94, v96
	v_add_f32_e32 v77, v88, v92
	v_add_f32_e32 v78, v78, v86
	v_add_f32_e32 v66, v66, v76
	v_add_f32_e32 v67, v77, v67
	v_add_f32_e32 v66, v66, v78
	v_add_f32_e32 v76, v66, v67
	v_mov_b32_e32 v77, v76
	s_nop 1
	v_permlane16_swap_b32_e32 v76, v77
	v_cvt_pk_bf16_f32 v66, v72, v73
	v_cvt_pk_bf16_f32 v67, v74, v75
	global_store_dwordx4 v[90:91], v[64:67], off
	s_waitcnt lgkmcnt(0)
	s_nop 0
	v_add_f32_e32 v64, v76, v77
	v_mov_b32_e32 v65, v64
	s_nop 1
	v_permlane32_swap_b32_e32 v64, v65
	v_cvt_pk_bf16_f32 v66, v68, v69
	v_cvt_pk_bf16_f32 v67, v70, v71
	v_cvt_pk_bf16_f32 v68, v82, v83
	v_cvt_pk_bf16_f32 v69, v84, v85
	global_store_dwordx4 v[90:91], v[66:69], off offset:256
	s_and_saveexec_b64 s[26:27], s[4:5]
	s_cbranch_execz .LBB0_720
	v_lshlrev_b64 v[66:67], 6, v[80:81]
	v_lshl_add_u64 v[66:67], s[16:17], 0, v[66:67]
	v_lshl_add_u64 v[66:67], s[24:25], 2, v[66:67]
	s_lshl_b32 s10, s40, 2
	v_lshl_add_u64 v[66:67], v[66:67], 0, s[10:11]
	s_waitcnt lgkmcnt(0)
	v_add_f32_e32 v64, v64, v65
	global_store_dword v[66:67], v64, off
.LBB0_720:
	s_or_b64 exec, exec, s[26:27]
	v_add_u32_e32 v64, 0x80, v150
	s_waitcnt lgkmcnt(0)
	v_ashrrev_i32_e32 v65, 31, v64
	v_lshlrev_b64 v[66:67], 11, v[64:65]
	v_lshl_add_u64 v[66:67], s[14:15], 0, v[66:67]
	v_lshl_add_u64 v[74:75], v[148:149], 1, v[66:67]
	s_nop 1
	v_mov_b32_e32 v66, v208
	v_mov_b32_e32 v67, v209
	v_mov_b32_e32 v68, v210
	v_mov_b32_e32 v69, v211
	v_mov_b32_e32 v70, v212
	v_mov_b32_e32 v71, v213
	v_mov_b32_e32 v72, v214
	v_mov_b32_e32 v73, v215
	v_lshlrev_b32_e32 v76, 16, v66
	v_and_b32_e32 v77, 0xffff0000, v66
	v_lshlrev_b32_e32 v66, 16, v67
	v_and_b32_e32 v67, 0xffff0000, v67
	v_lshlrev_b32_e32 v78, 16, v68
	v_and_b32_e32 v79, 0xffff0000, v68
	v_lshlrev_b32_e32 v68, 16, v69
	v_and_b32_e32 v69, 0xffff0000, v69
	v_lshlrev_b32_e32 v80, 16, v70
	v_and_b32_e32 v81, 0xffff0000, v70
	v_lshlrev_b32_e32 v70, 16, v71
	v_and_b32_e32 v71, 0xffff0000, v71
	v_lshlrev_b32_e32 v82, 16, v72
	v_and_b32_e32 v83, 0xffff0000, v72
	v_lshlrev_b32_e32 v72, 16, v73
	v_and_b32_e32 v73, 0xffff0000, v73
	v_pk_add_f32 v[60:61], v[60:61], v[76:77]
	v_pk_add_f32 v[62:63], v[62:63], v[66:67]
	v_pk_add_f32 v[56:57], v[56:57], v[78:79]
	v_pk_add_f32 v[58:59], v[58:59], v[68:69]
	v_pk_add_f32 v[52:53], v[52:53], v[80:81]
	v_pk_add_f32 v[54:55], v[54:55], v[70:71]
	v_pk_add_f32 v[66:67], v[48:49], v[82:83]
	v_pk_add_f32 v[68:69], v[50:51], v[72:73]
	v_cvt_pk_bf16_f32 v48, v60, v61
	v_cvt_pk_bf16_f32 v49, v62, v63
	v_pk_mul_f32 v[50:51], v[60:61], v[60:61]
	v_pk_mul_f32 v[60:61], v[62:63], v[62:63]
	v_pk_mul_f32 v[62:63], v[56:57], v[56:57]
	v_pk_mul_f32 v[70:71], v[58:59], v[58:59]
	v_pk_mul_f32 v[72:73], v[52:53], v[52:53]
	v_pk_mul_f32 v[76:77], v[54:55], v[54:55]
	v_pk_mul_f32 v[78:79], v[66:67], v[66:67]
	v_pk_mul_f32 v[80:81], v[68:69], v[68:69]
	v_add_f32_e32 v78, v78, v79
	v_add_f32_e32 v80, v80, v81
	v_add_f32_e32 v76, v76, v77
	v_add_f32_e32 v72, v72, v73
	v_add_f32_e32 v70, v70, v71
	v_add_f32_e32 v62, v62, v63
	v_add_f32_e32 v60, v60, v61
	v_add_f32_e32 v50, v50, v51
	v_add_f32_e32 v51, v78, v80
	v_add_f32_e32 v61, v72, v76
	v_add_f32_e32 v62, v62, v70
	v_add_f32_e32 v50, v50, v60
	v_add_f32_e32 v51, v61, v51
	v_add_f32_e32 v50, v50, v62
	v_add_f32_e32 v60, v50, v51
	v_mov_b32_e32 v61, v60
	s_nop 1
	v_permlane16_swap_b32_e32 v60, v61
	v_cvt_pk_bf16_f32 v50, v56, v57
	v_cvt_pk_bf16_f32 v51, v58, v59
	global_store_dwordx4 v[74:75], v[48:51], off
	s_waitcnt lgkmcnt(0)
	s_nop 0
	v_add_f32_e32 v48, v60, v61
	v_mov_b32_e32 v49, v48
	s_nop 1
	v_permlane32_swap_b32_e32 v48, v49
	v_cvt_pk_bf16_f32 v50, v52, v53
	v_cvt_pk_bf16_f32 v51, v54, v55
	v_cvt_pk_bf16_f32 v52, v66, v67
	v_cvt_pk_bf16_f32 v53, v68, v69
	global_store_dwordx4 v[74:75], v[50:53], off offset:256
	s_and_saveexec_b64 s[26:27], s[4:5]
	s_cbranch_execz .LBB0_722
	v_lshlrev_b64 v[50:51], 6, v[64:65]
	v_lshl_add_u64 v[50:51], s[16:17], 0, v[50:51]
	v_lshl_add_u64 v[50:51], s[24:25], 2, v[50:51]
	s_lshl_b32 s10, s40, 2
	v_lshl_add_u64 v[50:51], v[50:51], 0, s[10:11]
	s_waitcnt lgkmcnt(0)
	v_add_f32_e32 v48, v48, v49
	global_store_dword v[50:51], v48, off
.LBB0_722:
	s_or_b64 exec, exec, s[26:27]
	v_add_u32_e32 v48, 0x90, v150
	s_waitcnt lgkmcnt(0)
	v_ashrrev_i32_e32 v49, 31, v48
	v_lshlrev_b64 v[50:51], 11, v[48:49]
	v_lshl_add_u64 v[50:51], s[14:15], 0, v[50:51]
	v_lshl_add_u64 v[58:59], v[148:149], 1, v[50:51]
	s_nop 1
	v_mov_b32_e32 v50, v216
	v_mov_b32_e32 v51, v217
	v_mov_b32_e32 v52, v218
	v_mov_b32_e32 v53, v219
	v_mov_b32_e32 v54, v220
	v_mov_b32_e32 v55, v221
	v_mov_b32_e32 v56, v222
	v_mov_b32_e32 v57, v223
	v_lshlrev_b32_e32 v60, 16, v50
	v_and_b32_e32 v61, 0xffff0000, v50
	v_lshlrev_b32_e32 v50, 16, v51
	v_and_b32_e32 v51, 0xffff0000, v51
	v_lshlrev_b32_e32 v62, 16, v52
	v_and_b32_e32 v63, 0xffff0000, v52
	v_lshlrev_b32_e32 v52, 16, v53
	v_and_b32_e32 v53, 0xffff0000, v53
	v_lshlrev_b32_e32 v64, 16, v54
	v_and_b32_e32 v65, 0xffff0000, v54
	v_lshlrev_b32_e32 v54, 16, v55
	v_and_b32_e32 v55, 0xffff0000, v55
	v_lshlrev_b32_e32 v66, 16, v56
	v_and_b32_e32 v67, 0xffff0000, v56
	v_lshlrev_b32_e32 v56, 16, v57
	v_and_b32_e32 v57, 0xffff0000, v57
	v_pk_add_f32 v[44:45], v[44:45], v[60:61]
	v_pk_add_f32 v[46:47], v[46:47], v[50:51]
	v_pk_add_f32 v[40:41], v[40:41], v[62:63]
	v_pk_add_f32 v[42:43], v[42:43], v[52:53]
	v_pk_add_f32 v[36:37], v[36:37], v[64:65]
	v_pk_add_f32 v[38:39], v[38:39], v[54:55]
	v_pk_add_f32 v[50:51], v[32:33], v[66:67]
	v_pk_add_f32 v[52:53], v[34:35], v[56:57]
	v_cvt_pk_bf16_f32 v32, v44, v45
	v_cvt_pk_bf16_f32 v33, v46, v47
	v_pk_mul_f32 v[34:35], v[44:45], v[44:45]
	v_pk_mul_f32 v[44:45], v[46:47], v[46:47]
	v_pk_mul_f32 v[46:47], v[40:41], v[40:41]
	v_pk_mul_f32 v[54:55], v[42:43], v[42:43]
	v_pk_mul_f32 v[56:57], v[36:37], v[36:37]
	v_pk_mul_f32 v[60:61], v[38:39], v[38:39]
	v_pk_mul_f32 v[62:63], v[50:51], v[50:51]
	v_pk_mul_f32 v[64:65], v[52:53], v[52:53]
	v_add_f32_e32 v62, v62, v63
	v_add_f32_e32 v64, v64, v65
	v_add_f32_e32 v60, v60, v61
	v_add_f32_e32 v56, v56, v57
	v_add_f32_e32 v54, v54, v55
	v_add_f32_e32 v46, v46, v47
	v_add_f32_e32 v44, v44, v45
	v_add_f32_e32 v34, v34, v35
	v_add_f32_e32 v35, v62, v64
	v_add_f32_e32 v45, v56, v60
	v_add_f32_e32 v46, v46, v54
	v_add_f32_e32 v34, v34, v44
	v_add_f32_e32 v35, v45, v35
	v_add_f32_e32 v34, v34, v46
	v_add_f32_e32 v44, v34, v35
	v_mov_b32_e32 v45, v44
	s_nop 1
	v_permlane16_swap_b32_e32 v44, v45
	v_cvt_pk_bf16_f32 v34, v40, v41
	v_cvt_pk_bf16_f32 v35, v42, v43
	global_store_dwordx4 v[58:59], v[32:35], off
	s_waitcnt lgkmcnt(0)
	s_nop 0
	v_add_f32_e32 v32, v44, v45
	v_mov_b32_e32 v33, v32
	s_nop 1
	v_permlane32_swap_b32_e32 v32, v33
	v_cvt_pk_bf16_f32 v34, v36, v37
	v_cvt_pk_bf16_f32 v35, v38, v39
	v_cvt_pk_bf16_f32 v36, v50, v51
	v_cvt_pk_bf16_f32 v37, v52, v53
	global_store_dwordx4 v[58:59], v[34:37], off offset:256
	s_and_saveexec_b64 s[26:27], s[4:5]
	s_cbranch_execz .LBB0_724
	v_lshlrev_b64 v[34:35], 6, v[48:49]
	v_lshl_add_u64 v[34:35], s[16:17], 0, v[34:35]
	v_lshl_add_u64 v[34:35], s[24:25], 2, v[34:35]
	s_lshl_b32 s10, s40, 2
	v_lshl_add_u64 v[34:35], v[34:35], 0, s[10:11]
	s_waitcnt lgkmcnt(0)
	v_add_f32_e32 v32, v32, v33
	global_store_dword v[34:35], v32, off
.LBB0_724:
	s_or_b64 exec, exec, s[26:27]
	v_add_u32_e32 v32, 0xa0, v150
	s_waitcnt lgkmcnt(0)
	v_ashrrev_i32_e32 v33, 31, v32
	v_lshlrev_b64 v[34:35], 11, v[32:33]
	v_lshl_add_u64 v[34:35], s[14:15], 0, v[34:35]
	v_lshl_add_u64 v[42:43], v[148:149], 1, v[34:35]
	s_nop 1
	v_mov_b32_e32 v34, v224
	v_mov_b32_e32 v35, v225
	v_mov_b32_e32 v36, v226
	v_mov_b32_e32 v37, v227
	v_mov_b32_e32 v38, v228
	v_mov_b32_e32 v39, v229
	v_mov_b32_e32 v40, v230
	v_mov_b32_e32 v41, v231
	v_lshlrev_b32_e32 v44, 16, v34
	v_and_b32_e32 v45, 0xffff0000, v34
	v_lshlrev_b32_e32 v34, 16, v35
	v_and_b32_e32 v35, 0xffff0000, v35
	v_lshlrev_b32_e32 v46, 16, v36
	v_and_b32_e32 v47, 0xffff0000, v36
	v_lshlrev_b32_e32 v36, 16, v37
	v_and_b32_e32 v37, 0xffff0000, v37
	v_lshlrev_b32_e32 v48, 16, v38
	v_and_b32_e32 v49, 0xffff0000, v38
	v_lshlrev_b32_e32 v38, 16, v39
	v_and_b32_e32 v39, 0xffff0000, v39
	v_lshlrev_b32_e32 v50, 16, v40
	v_and_b32_e32 v51, 0xffff0000, v40
	v_lshlrev_b32_e32 v40, 16, v41
	v_and_b32_e32 v41, 0xffff0000, v41
	v_pk_add_f32 v[28:29], v[28:29], v[44:45]
	v_pk_add_f32 v[30:31], v[30:31], v[34:35]
	v_pk_add_f32 v[24:25], v[24:25], v[46:47]
	v_pk_add_f32 v[26:27], v[26:27], v[36:37]
	v_pk_add_f32 v[20:21], v[20:21], v[48:49]
	v_pk_add_f32 v[22:23], v[22:23], v[38:39]
	v_pk_add_f32 v[34:35], v[16:17], v[50:51]
	v_pk_add_f32 v[36:37], v[18:19], v[40:41]
	v_cvt_pk_bf16_f32 v16, v28, v29
	v_cvt_pk_bf16_f32 v17, v30, v31
	v_pk_mul_f32 v[18:19], v[28:29], v[28:29]
	v_pk_mul_f32 v[28:29], v[30:31], v[30:31]
	v_pk_mul_f32 v[30:31], v[24:25], v[24:25]
	v_pk_mul_f32 v[38:39], v[26:27], v[26:27]
	v_pk_mul_f32 v[40:41], v[20:21], v[20:21]
	v_pk_mul_f32 v[44:45], v[22:23], v[22:23]
	v_pk_mul_f32 v[46:47], v[34:35], v[34:35]
	v_pk_mul_f32 v[48:49], v[36:37], v[36:37]
	v_add_f32_e32 v46, v46, v47
	v_add_f32_e32 v48, v48, v49
	v_add_f32_e32 v44, v44, v45
	v_add_f32_e32 v40, v40, v41
	v_add_f32_e32 v38, v38, v39
	v_add_f32_e32 v30, v30, v31
	v_add_f32_e32 v28, v28, v29
	v_add_f32_e32 v18, v18, v19
	v_add_f32_e32 v19, v46, v48
	v_add_f32_e32 v29, v40, v44
	v_add_f32_e32 v30, v30, v38
	v_add_f32_e32 v18, v18, v28
	v_add_f32_e32 v19, v29, v19
	v_add_f32_e32 v18, v18, v30
	v_add_f32_e32 v28, v18, v19
	v_mov_b32_e32 v29, v28
	s_nop 1
	v_permlane16_swap_b32_e32 v28, v29
	v_cvt_pk_bf16_f32 v18, v24, v25
	v_cvt_pk_bf16_f32 v19, v26, v27
	global_store_dwordx4 v[42:43], v[16:19], off
	s_waitcnt lgkmcnt(0)
	s_nop 0
	v_add_f32_e32 v16, v28, v29
	v_mov_b32_e32 v17, v16
	s_nop 1
	v_permlane32_swap_b32_e32 v16, v17
	v_cvt_pk_bf16_f32 v18, v20, v21
	v_cvt_pk_bf16_f32 v19, v22, v23
	v_cvt_pk_bf16_f32 v20, v34, v35
	v_cvt_pk_bf16_f32 v21, v36, v37
	global_store_dwordx4 v[42:43], v[18:21], off offset:256
	s_and_saveexec_b64 s[26:27], s[4:5]
	s_cbranch_execz .LBB0_726
	v_lshlrev_b64 v[18:19], 6, v[32:33]
	v_lshl_add_u64 v[18:19], s[16:17], 0, v[18:19]
	v_lshl_add_u64 v[18:19], s[24:25], 2, v[18:19]
	s_lshl_b32 s10, s40, 2
	v_lshl_add_u64 v[18:19], v[18:19], 0, s[10:11]
	s_waitcnt lgkmcnt(0)
	v_add_f32_e32 v16, v16, v17
	global_store_dword v[18:19], v16, off
.LBB0_726:
	s_or_b64 exec, exec, s[26:27]
	v_add_u32_e32 v16, 0xb0, v150
	s_waitcnt lgkmcnt(0)
	v_ashrrev_i32_e32 v17, 31, v16
	v_lshlrev_b64 v[18:19], 11, v[16:17]
	v_lshl_add_u64 v[18:19], s[14:15], 0, v[18:19]
	v_lshl_add_u64 v[26:27], v[148:149], 1, v[18:19]
	s_nop 1
	v_mov_b32_e32 v18, v238
	v_mov_b32_e32 v19, v239
	v_mov_b32_e32 v20, v240
	v_mov_b32_e32 v21, v241
	v_mov_b32_e32 v22, v242
	v_mov_b32_e32 v23, v243
	v_mov_b32_e32 v24, v244
	v_mov_b32_e32 v25, v245
	v_lshlrev_b32_e32 v28, 16, v18
	v_and_b32_e32 v29, 0xffff0000, v18
	v_lshlrev_b32_e32 v18, 16, v19
	v_and_b32_e32 v19, 0xffff0000, v19
	v_lshlrev_b32_e32 v30, 16, v20
	v_and_b32_e32 v31, 0xffff0000, v20
	v_lshlrev_b32_e32 v20, 16, v21
	v_and_b32_e32 v21, 0xffff0000, v21
	v_lshlrev_b32_e32 v32, 16, v22
	v_and_b32_e32 v33, 0xffff0000, v22
	v_lshlrev_b32_e32 v22, 16, v23
	v_and_b32_e32 v23, 0xffff0000, v23
	v_lshlrev_b32_e32 v34, 16, v24
	v_and_b32_e32 v35, 0xffff0000, v24
	v_lshlrev_b32_e32 v24, 16, v25
	v_and_b32_e32 v25, 0xffff0000, v25
	v_pk_add_f32 v[12:13], v[12:13], v[28:29]
	v_pk_add_f32 v[14:15], v[14:15], v[18:19]
	v_pk_add_f32 v[8:9], v[8:9], v[30:31]
	v_pk_add_f32 v[10:11], v[10:11], v[20:21]
	v_pk_add_f32 v[4:5], v[4:5], v[32:33]
	v_pk_add_f32 v[6:7], v[6:7], v[22:23]
	v_pk_add_f32 v[18:19], v[0:1], v[34:35]
	v_pk_add_f32 v[20:21], v[2:3], v[24:25]
	v_cvt_pk_bf16_f32 v0, v12, v13
	v_cvt_pk_bf16_f32 v1, v14, v15
	v_pk_mul_f32 v[2:3], v[12:13], v[12:13]
	v_pk_mul_f32 v[12:13], v[14:15], v[14:15]
	v_pk_mul_f32 v[14:15], v[8:9], v[8:9]
	v_pk_mul_f32 v[22:23], v[10:11], v[10:11]
	v_pk_mul_f32 v[24:25], v[4:5], v[4:5]
	v_pk_mul_f32 v[28:29], v[6:7], v[6:7]
	v_pk_mul_f32 v[30:31], v[18:19], v[18:19]
	v_pk_mul_f32 v[32:33], v[20:21], v[20:21]
	v_add_f32_e32 v30, v30, v31
	v_add_f32_e32 v32, v32, v33
	v_add_f32_e32 v28, v28, v29
	v_add_f32_e32 v24, v24, v25
	v_add_f32_e32 v22, v22, v23
	v_add_f32_e32 v14, v14, v15
	v_add_f32_e32 v12, v12, v13
	v_add_f32_e32 v2, v2, v3
	v_add_f32_e32 v3, v30, v32
	v_add_f32_e32 v13, v24, v28
	v_add_f32_e32 v14, v14, v22
	v_add_f32_e32 v2, v2, v12
	v_add_f32_e32 v3, v13, v3
	v_add_f32_e32 v2, v2, v14
	v_add_f32_e32 v12, v2, v3
	v_mov_b32_e32 v13, v12
	s_nop 1
	v_permlane16_swap_b32_e32 v12, v13
	v_cvt_pk_bf16_f32 v2, v8, v9
	v_cvt_pk_bf16_f32 v3, v10, v11
	global_store_dwordx4 v[26:27], v[0:3], off
	s_waitcnt lgkmcnt(0)
	s_nop 0
	v_add_f32_e32 v0, v12, v13
	v_mov_b32_e32 v1, v0
	s_nop 1
	v_permlane32_swap_b32_e32 v0, v1
	v_cvt_pk_bf16_f32 v2, v4, v5
	v_cvt_pk_bf16_f32 v3, v6, v7
	v_cvt_pk_bf16_f32 v4, v18, v19
	v_cvt_pk_bf16_f32 v5, v20, v21
	global_store_dwordx4 v[26:27], v[2:5], off offset:256
	s_and_saveexec_b64 s[26:27], s[4:5]
	s_cbranch_execz .LBB0_728
	v_lshlrev_b64 v[2:3], 6, v[16:17]
	v_lshl_add_u64 v[2:3], s[16:17], 0, v[2:3]
	v_lshl_add_u64 v[2:3], s[24:25], 2, v[2:3]
	s_lshl_b32 s10, s40, 2
	v_lshl_add_u64 v[2:3], v[2:3], 0, s[10:11]
	s_waitcnt lgkmcnt(0)
	v_add_f32_e32 v0, v0, v1
	global_store_dword v[2:3], v0, off

.LBB0_1151:
	v_lshl_add_u32 v150, s28, 8, v131
	v_ashrrev_i32_e32 v151, 31, v150
	v_lshl_or_b32 v148, s8, 8, v153
	v_lshlrev_b64 v[158:159], 11, v[150:151]
	v_ashrrev_i32_e32 v149, 31, v148
	v_lshl_add_u64 v[158:159], s[12:13], 0, v[158:159]
	v_lshl_add_u64 v[168:169], v[148:149], 1, v[158:159]
	global_load_dwordx4 v[160:163], v[168:169], off
	global_load_dwordx4 v[164:167], v[168:169], off offset:256
	s_mov_b64 s[100:101], 0x8000
	v_lshl_add_u64 v[232:233], v[168:169], 0, s[100:101]
	global_load_dwordx4 v[184:187], v[232:233], off
	global_load_dwordx4 v[188:191], v[232:233], off offset:256
	s_mov_b64 s[100:101], 0x10000
	v_lshl_add_u64 v[232:233], v[168:169], 0, s[100:101]
	global_load_dwordx4 v[192:195], v[232:233], off
	global_load_dwordx4 v[196:199], v[232:233], off offset:256
	s_mov_b64 s[100:101], 0x18000
	v_lshl_add_u64 v[232:233], v[168:169], 0, s[100:101]
	global_load_dwordx4 v[200:203], v[232:233], off
	global_load_dwordx4 v[204:207], v[232:233], off offset:256
	s_mov_b64 s[100:101], 0x40000
	v_lshl_add_u64 v[232:233], v[168:169], 0, s[100:101]
	global_load_dwordx4 v[208:211], v[232:233], off
	global_load_dwordx4 v[212:215], v[232:233], off offset:256
	s_mov_b64 s[100:101], 0x48000
	v_lshl_add_u64 v[232:233], v[168:169], 0, s[100:101]
	global_load_dwordx4 v[216:219], v[232:233], off
	global_load_dwordx4 v[220:223], v[232:233], off offset:256
	s_mov_b64 s[100:101], 0x50000
	v_lshl_add_u64 v[232:233], v[168:169], 0, s[100:101]
	global_load_dwordx4 v[224:227], v[232:233], off
	global_load_dwordx4 v[228:231], v[232:233], off offset:256
	s_mov_b64 s[100:101], 0x58000
	v_lshl_add_u64 v[232:233], v[168:169], 0, s[100:101]
	global_load_dwordx4 v[238:241], v[232:233], off
	global_load_dwordx4 v[242:245], v[232:233], off offset:256
	v_and_b32_e32 v159, 64, v157
	v_xor_b32_e32 v158, 16, v157
	v_add_u32_e32 v159, 64, v159
	v_xor_b32_e32 v170, 32, v157
	v_cmp_lt_i32_e32 vcc, v158, v159
	s_lshl_b32 s28, s8, 2
	s_ashr_i32 s29, s28, 31
	v_cndmask_b32_e32 v158, v157, v158, vcc
	v_cmp_lt_i32_e32 vcc, v170, v159
	v_lshlrev_b32_e32 v159, 2, v158
	s_waitcnt vmcnt(0)
	v_and_b32_e32 v171, 0xffff0000, v160
	v_cndmask_b32_e32 v170, v157, v170, vcc
	v_lshlrev_b32_e32 v158, 2, v170
	v_lshlrev_b32_e32 v170, 16, v160
	v_lshlrev_b32_e32 v160, 16, v161
	v_and_b32_e32 v161, 0xffff0000, v161
	v_lshlrev_b32_e32 v172, 16, v162
	v_and_b32_e32 v173, 0xffff0000, v162
	v_lshlrev_b32_e32 v162, 16, v163
	v_and_b32_e32 v163, 0xffff0000, v163
	v_lshlrev_b32_e32 v174, 16, v164
	v_and_b32_e32 v175, 0xffff0000, v164
	v_lshlrev_b32_e32 v164, 16, v165
	v_and_b32_e32 v165, 0xffff0000, v165
	v_lshlrev_b32_e32 v176, 16, v166
	v_and_b32_e32 v177, 0xffff0000, v166
	v_lshlrev_b32_e32 v166, 16, v167
	v_and_b32_e32 v167, 0xffff0000, v167
	v_pk_add_f32 v[124:125], v[124:125], v[170:171]
	v_pk_add_f32 v[126:127], v[126:127], v[160:161]
	v_pk_add_f32 v[120:121], v[120:121], v[172:173]
	v_pk_add_f32 v[122:123], v[122:123], v[162:163]
	v_pk_add_f32 v[116:117], v[116:117], v[174:175]
	v_pk_add_f32 v[118:119], v[118:119], v[164:165]
	v_pk_add_f32 v[160:161], v[112:113], v[176:177]
	v_pk_add_f32 v[162:163], v[114:115], v[166:167]
	v_cvt_pk_bf16_f32 v112, v124, v125
	v_cvt_pk_bf16_f32 v113, v126, v127
	v_pk_mul_f32 v[114:115], v[124:125], v[124:125]
	v_pk_mul_f32 v[124:125], v[126:127], v[126:127]
	v_pk_mul_f32 v[126:127], v[120:121], v[120:121]
	v_pk_mul_f32 v[164:165], v[122:123], v[122:123]
	v_pk_mul_f32 v[166:167], v[116:117], v[116:117]
	v_pk_mul_f32 v[170:171], v[118:119], v[118:119]
	v_pk_mul_f32 v[172:173], v[160:161], v[160:161]
	v_pk_mul_f32 v[174:175], v[162:163], v[162:163]
	v_add_f32_e32 v172, v172, v173
	v_add_f32_e32 v174, v174, v175
	v_add_f32_e32 v170, v170, v171
	v_add_f32_e32 v166, v166, v167
	v_add_f32_e32 v164, v164, v165
	v_add_f32_e32 v126, v126, v127
	v_add_f32_e32 v124, v124, v125
	v_add_f32_e32 v114, v114, v115
	v_add_f32_e32 v115, v172, v174
	v_add_f32_e32 v125, v166, v170
	v_add_f32_e32 v126, v126, v164
	v_add_f32_e32 v114, v114, v124
	v_add_f32_e32 v115, v125, v115
	v_add_f32_e32 v114, v114, v126
	v_add_f32_e32 v124, v114, v115
	v_mov_b32_e32 v125, v124
	s_nop 1
	v_permlane16_swap_b32_e32 v124, v125
	v_cvt_pk_bf16_f32 v114, v120, v121
	v_cvt_pk_bf16_f32 v115, v122, v123
	global_store_dwordx4 v[168:169], v[112:115], off
	s_waitcnt lgkmcnt(0)
	s_nop 0
	v_add_f32_e32 v112, v124, v125
	v_mov_b32_e32 v113, v112
	s_nop 1
	v_permlane32_swap_b32_e32 v112, v113
	v_cvt_pk_bf16_f32 v114, v116, v117
	v_cvt_pk_bf16_f32 v115, v118, v119
	v_cvt_pk_bf16_f32 v116, v160, v161
	v_cvt_pk_bf16_f32 v117, v162, v163
	global_store_dwordx4 v[168:169], v[114:117], off offset:256
	s_and_saveexec_b64 s[30:31], s[4:5]
	s_cbranch_execz .LBB0_1153
	v_lshlrev_b64 v[114:115], 6, v[150:151]
	v_lshl_add_u64 v[114:115], s[14:15], 0, v[114:115]
	v_lshl_add_u64 v[114:115], s[28:29], 2, v[114:115]
	s_lshl_b32 s8, s46, 2
	v_lshl_add_u64 v[114:115], v[114:115], 0, s[8:9]
	s_waitcnt lgkmcnt(0)
	v_add_f32_e32 v112, v112, v113
	global_store_dword v[114:115], v112, off
.LBB0_1153:
	s_or_b64 exec, exec, s[30:31]
	v_or_b32_e32 v112, 16, v150
	s_waitcnt lgkmcnt(0)
	v_ashrrev_i32_e32 v113, 31, v112
	v_lshlrev_b64 v[114:115], 11, v[112:113]
	v_lshl_add_u64 v[114:115], s[12:13], 0, v[114:115]
	v_lshl_add_u64 v[122:123], v[148:149], 1, v[114:115]
	s_nop 1
	v_mov_b32_e32 v114, v184
	v_mov_b32_e32 v115, v185
	v_mov_b32_e32 v116, v186
	v_mov_b32_e32 v117, v187
	v_mov_b32_e32 v118, v188
	v_mov_b32_e32 v119, v189
	v_mov_b32_e32 v120, v190
	v_mov_b32_e32 v121, v191
	v_lshlrev_b32_e32 v124, 16, v114
	v_and_b32_e32 v125, 0xffff0000, v114
	v_lshlrev_b32_e32 v114, 16, v115
	v_and_b32_e32 v115, 0xffff0000, v115
	v_lshlrev_b32_e32 v126, 16, v116
	v_and_b32_e32 v127, 0xffff0000, v116
	v_lshlrev_b32_e32 v116, 16, v117
	v_and_b32_e32 v117, 0xffff0000, v117
	v_lshlrev_b32_e32 v160, 16, v118
	v_and_b32_e32 v161, 0xffff0000, v118
	v_lshlrev_b32_e32 v118, 16, v119
	v_and_b32_e32 v119, 0xffff0000, v119
	v_lshlrev_b32_e32 v162, 16, v120
	v_and_b32_e32 v163, 0xffff0000, v120
	v_lshlrev_b32_e32 v120, 16, v121
	v_and_b32_e32 v121, 0xffff0000, v121
	v_pk_add_f32 v[108:109], v[108:109], v[124:125]
	v_pk_add_f32 v[110:111], v[110:111], v[114:115]
	v_pk_add_f32 v[104:105], v[104:105], v[126:127]
	v_pk_add_f32 v[106:107], v[106:107], v[116:117]
	v_pk_add_f32 v[100:101], v[100:101], v[160:161]
	v_pk_add_f32 v[102:103], v[102:103], v[118:119]
	v_pk_add_f32 v[114:115], v[96:97], v[162:163]
	v_pk_add_f32 v[116:117], v[98:99], v[120:121]
	v_cvt_pk_bf16_f32 v96, v108, v109
	v_cvt_pk_bf16_f32 v97, v110, v111
	v_pk_mul_f32 v[98:99], v[108:109], v[108:109]
	v_pk_mul_f32 v[108:109], v[110:111], v[110:111]
	v_pk_mul_f32 v[110:111], v[104:105], v[104:105]
	v_pk_mul_f32 v[118:119], v[106:107], v[106:107]
	v_pk_mul_f32 v[120:121], v[100:101], v[100:101]
	v_pk_mul_f32 v[124:125], v[102:103], v[102:103]
	v_pk_mul_f32 v[126:127], v[114:115], v[114:115]
	v_pk_mul_f32 v[160:161], v[116:117], v[116:117]
	v_add_f32_e32 v126, v126, v127
	v_add_f32_e32 v151, v160, v161
	v_add_f32_e32 v124, v124, v125
	v_add_f32_e32 v120, v120, v121
	v_add_f32_e32 v118, v118, v119
	v_add_f32_e32 v110, v110, v111
	v_add_f32_e32 v108, v108, v109
	v_add_f32_e32 v98, v98, v99
	v_add_f32_e32 v99, v126, v151
	v_add_f32_e32 v109, v120, v124
	v_add_f32_e32 v110, v110, v118
	v_add_f32_e32 v98, v98, v108
	v_add_f32_e32 v99, v109, v99
	v_add_f32_e32 v98, v98, v110
	v_add_f32_e32 v108, v98, v99
	v_mov_b32_e32 v109, v108
	s_nop 1
	v_permlane16_swap_b32_e32 v108, v109
	v_cvt_pk_bf16_f32 v98, v104, v105
	v_cvt_pk_bf16_f32 v99, v106, v107
	global_store_dwordx4 v[122:123], v[96:99], off
	s_waitcnt lgkmcnt(0)
	s_nop 0
	v_add_f32_e32 v96, v108, v109
	v_mov_b32_e32 v97, v96
	s_nop 1
	v_permlane32_swap_b32_e32 v96, v97
	v_cvt_pk_bf16_f32 v98, v100, v101
	v_cvt_pk_bf16_f32 v99, v102, v103
	v_cvt_pk_bf16_f32 v100, v114, v115
	v_cvt_pk_bf16_f32 v101, v116, v117
	global_store_dwordx4 v[122:123], v[98:101], off offset:256
	s_and_saveexec_b64 s[30:31], s[4:5]
	s_cbranch_execz .LBB0_1155
	v_lshlrev_b64 v[98:99], 6, v[112:113]
	v_lshl_add_u64 v[98:99], s[14:15], 0, v[98:99]
	v_lshl_add_u64 v[98:99], s[28:29], 2, v[98:99]
	s_lshl_b32 s8, s46, 2
	v_lshl_add_u64 v[98:99], v[98:99], 0, s[8:9]
	s_waitcnt lgkmcnt(0)
	v_add_f32_e32 v96, v96, v97
	global_store_dword v[98:99], v96, off
.LBB0_1155:
	s_or_b64 exec, exec, s[30:31]
	v_or_b32_e32 v96, 32, v150
	s_waitcnt lgkmcnt(0)
	v_ashrrev_i32_e32 v97, 31, v96
	v_lshlrev_b64 v[98:99], 11, v[96:97]
	v_lshl_add_u64 v[98:99], s[12:13], 0, v[98:99]
	v_lshl_add_u64 v[106:107], v[148:149], 1, v[98:99]
	s_nop 1
	v_mov_b32_e32 v98, v192
	v_mov_b32_e32 v99, v193
	v_mov_b32_e32 v100, v194
	v_mov_b32_e32 v101, v195
	v_mov_b32_e32 v102, v196
	v_mov_b32_e32 v103, v197
	v_mov_b32_e32 v104, v198
	v_mov_b32_e32 v105, v199
	v_lshlrev_b32_e32 v108, 16, v98
	v_and_b32_e32 v109, 0xffff0000, v98
	v_lshlrev_b32_e32 v98, 16, v99
	v_and_b32_e32 v99, 0xffff0000, v99
	v_lshlrev_b32_e32 v110, 16, v100
	v_and_b32_e32 v111, 0xffff0000, v100
	v_lshlrev_b32_e32 v100, 16, v101
	v_and_b32_e32 v101, 0xffff0000, v101
	v_lshlrev_b32_e32 v112, 16, v102
	v_and_b32_e32 v113, 0xffff0000, v102
	v_lshlrev_b32_e32 v102, 16, v103
	v_and_b32_e32 v103, 0xffff0000, v103
	v_lshlrev_b32_e32 v114, 16, v104
	v_and_b32_e32 v115, 0xffff0000, v104
	v_lshlrev_b32_e32 v104, 16, v105
	v_and_b32_e32 v105, 0xffff0000, v105
	v_pk_add_f32 v[92:93], v[92:93], v[108:109]
	v_pk_add_f32 v[94:95], v[94:95], v[98:99]
	v_pk_add_f32 v[88:89], v[88:89], v[110:111]
	v_pk_add_f32 v[90:91], v[90:91], v[100:101]
	v_pk_add_f32 v[84:85], v[84:85], v[112:113]
	v_pk_add_f32 v[86:87], v[86:87], v[102:103]
	v_pk_add_f32 v[98:99], v[80:81], v[114:115]
	v_pk_add_f32 v[100:101], v[82:83], v[104:105]
	v_cvt_pk_bf16_f32 v80, v92, v93
	v_cvt_pk_bf16_f32 v81, v94, v95
	v_pk_mul_f32 v[82:83], v[92:93], v[92:93]
	v_pk_mul_f32 v[92:93], v[94:95], v[94:95]
	v_pk_mul_f32 v[94:95], v[88:89], v[88:89]
	v_pk_mul_f32 v[102:103], v[90:91], v[90:91]
	v_pk_mul_f32 v[104:105], v[84:85], v[84:85]
	v_pk_mul_f32 v[108:109], v[86:87], v[86:87]
	v_pk_mul_f32 v[110:111], v[98:99], v[98:99]
	v_pk_mul_f32 v[112:113], v[100:101], v[100:101]
	v_add_f32_e32 v110, v110, v111
	v_add_f32_e32 v112, v112, v113
	v_add_f32_e32 v108, v108, v109
	v_add_f32_e32 v104, v104, v105
	v_add_f32_e32 v102, v102, v103
	v_add_f32_e32 v94, v94, v95
	v_add_f32_e32 v92, v92, v93
	v_add_f32_e32 v82, v82, v83
	v_add_f32_e32 v83, v110, v112
	v_add_f32_e32 v93, v104, v108
	v_add_f32_e32 v94, v94, v102
	v_add_f32_e32 v82, v82, v92
	v_add_f32_e32 v83, v93, v83
	v_add_f32_e32 v82, v82, v94
	v_add_f32_e32 v92, v82, v83
	v_mov_b32_e32 v93, v92
	s_nop 1
	v_permlane16_swap_b32_e32 v92, v93
	v_cvt_pk_bf16_f32 v82, v88, v89
	v_cvt_pk_bf16_f32 v83, v90, v91
	global_store_dwordx4 v[106:107], v[80:83], off
	s_waitcnt lgkmcnt(0)
	s_nop 0
	v_add_f32_e32 v80, v92, v93
	v_mov_b32_e32 v81, v80
	s_nop 1
	v_permlane32_swap_b32_e32 v80, v81
	v_cvt_pk_bf16_f32 v82, v84, v85
	v_cvt_pk_bf16_f32 v83, v86, v87
	v_cvt_pk_bf16_f32 v84, v98, v99
	v_cvt_pk_bf16_f32 v85, v100, v101
	global_store_dwordx4 v[106:107], v[82:85], off offset:256
	s_and_saveexec_b64 s[30:31], s[4:5]
	s_cbranch_execz .LBB0_1157
	v_lshlrev_b64 v[82:83], 6, v[96:97]
	v_lshl_add_u64 v[82:83], s[14:15], 0, v[82:83]
	v_lshl_add_u64 v[82:83], s[28:29], 2, v[82:83]
	s_lshl_b32 s8, s46, 2
	v_lshl_add_u64 v[82:83], v[82:83], 0, s[8:9]
	s_waitcnt lgkmcnt(0)
	v_add_f32_e32 v80, v80, v81
	global_store_dword v[82:83], v80, off
.LBB0_1157:
	s_or_b64 exec, exec, s[30:31]
	v_or_b32_e32 v80, 48, v150
	s_waitcnt lgkmcnt(0)
	v_ashrrev_i32_e32 v81, 31, v80
	v_lshlrev_b64 v[82:83], 11, v[80:81]
	v_lshl_add_u64 v[82:83], s[12:13], 0, v[82:83]
	v_lshl_add_u64 v[90:91], v[148:149], 1, v[82:83]
	s_nop 1
	v_mov_b32_e32 v82, v200
	v_mov_b32_e32 v83, v201
	v_mov_b32_e32 v84, v202
	v_mov_b32_e32 v85, v203
	v_mov_b32_e32 v86, v204
	v_mov_b32_e32 v87, v205
	v_mov_b32_e32 v88, v206
	v_mov_b32_e32 v89, v207
	v_lshlrev_b32_e32 v92, 16, v82
	v_and_b32_e32 v93, 0xffff0000, v82
	v_lshlrev_b32_e32 v82, 16, v83
	v_and_b32_e32 v83, 0xffff0000, v83
	v_lshlrev_b32_e32 v94, 16, v84
	v_and_b32_e32 v95, 0xffff0000, v84
	v_lshlrev_b32_e32 v84, 16, v85
	v_and_b32_e32 v85, 0xffff0000, v85
	v_lshlrev_b32_e32 v96, 16, v86
	v_and_b32_e32 v97, 0xffff0000, v86
	v_lshlrev_b32_e32 v86, 16, v87
	v_and_b32_e32 v87, 0xffff0000, v87
	v_lshlrev_b32_e32 v98, 16, v88
	v_and_b32_e32 v99, 0xffff0000, v88
	v_lshlrev_b32_e32 v88, 16, v89
	v_and_b32_e32 v89, 0xffff0000, v89
	v_pk_add_f32 v[76:77], v[76:77], v[92:93]
	v_pk_add_f32 v[78:79], v[78:79], v[82:83]
	v_pk_add_f32 v[72:73], v[72:73], v[94:95]
	v_pk_add_f32 v[74:75], v[74:75], v[84:85]
	v_pk_add_f32 v[68:69], v[68:69], v[96:97]
	v_pk_add_f32 v[70:71], v[70:71], v[86:87]
	v_pk_add_f32 v[82:83], v[64:65], v[98:99]
	v_pk_add_f32 v[84:85], v[66:67], v[88:89]
	v_cvt_pk_bf16_f32 v64, v76, v77
	v_cvt_pk_bf16_f32 v65, v78, v79
	v_pk_mul_f32 v[66:67], v[76:77], v[76:77]
	v_pk_mul_f32 v[76:77], v[78:79], v[78:79]
	v_pk_mul_f32 v[78:79], v[72:73], v[72:73]
	v_pk_mul_f32 v[86:87], v[74:75], v[74:75]
	v_pk_mul_f32 v[88:89], v[68:69], v[68:69]
	v_pk_mul_f32 v[92:93], v[70:71], v[70:71]
	v_pk_mul_f32 v[94:95], v[82:83], v[82:83]
	v_pk_mul_f32 v[96:97], v[84:85], v[84:85]
	v_add_f32_e32 v94, v94, v95
	v_add_f32_e32 v96, v96, v97
	v_add_f32_e32 v92, v92, v93
	v_add_f32_e32 v88, v88, v89
	v_add_f32_e32 v86, v86, v87
	v_add_f32_e32 v78, v78, v79
	v_add_f32_e32 v76, v76, v77
	v_add_f32_e32 v66, v66, v67
	v_add_f32_e32 v67, v94, v96
	v_add_f32_e32 v77, v88, v92
	v_add_f32_e32 v78, v78, v86
	v_add_f32_e32 v66, v66, v76
	v_add_f32_e32 v67, v77, v67
	v_add_f32_e32 v66, v66, v78
	v_add_f32_e32 v76, v66, v67
	v_mov_b32_e32 v77, v76
	s_nop 1
	v_permlane16_swap_b32_e32 v76, v77
	v_cvt_pk_bf16_f32 v66, v72, v73
	v_cvt_pk_bf16_f32 v67, v74, v75
	global_store_dwordx4 v[90:91], v[64:67], off
	s_waitcnt lgkmcnt(0)
	s_nop 0
	v_add_f32_e32 v64, v76, v77
	v_mov_b32_e32 v65, v64
	s_nop 1
	v_permlane32_swap_b32_e32 v64, v65
	v_cvt_pk_bf16_f32 v66, v68, v69
	v_cvt_pk_bf16_f32 v67, v70, v71
	v_cvt_pk_bf16_f32 v68, v82, v83
	v_cvt_pk_bf16_f32 v69, v84, v85
	global_store_dwordx4 v[90:91], v[66:69], off offset:256
	s_and_saveexec_b64 s[30:31], s[4:5]
	s_cbranch_execz .LBB0_1159
	v_lshlrev_b64 v[66:67], 6, v[80:81]
	v_lshl_add_u64 v[66:67], s[14:15], 0, v[66:67]
	v_lshl_add_u64 v[66:67], s[28:29], 2, v[66:67]
	s_lshl_b32 s8, s46, 2
	v_lshl_add_u64 v[66:67], v[66:67], 0, s[8:9]
	s_waitcnt lgkmcnt(0)
	v_add_f32_e32 v64, v64, v65
	global_store_dword v[66:67], v64, off
.LBB0_1159:
	s_or_b64 exec, exec, s[30:31]
	v_add_u32_e32 v64, 0x80, v150
	s_waitcnt lgkmcnt(0)
	v_ashrrev_i32_e32 v65, 31, v64
	v_lshlrev_b64 v[66:67], 11, v[64:65]
	v_lshl_add_u64 v[66:67], s[12:13], 0, v[66:67]
	v_lshl_add_u64 v[74:75], v[148:149], 1, v[66:67]
	s_nop 1
	v_mov_b32_e32 v66, v208
	v_mov_b32_e32 v67, v209
	v_mov_b32_e32 v68, v210
	v_mov_b32_e32 v69, v211
	v_mov_b32_e32 v70, v212
	v_mov_b32_e32 v71, v213
	v_mov_b32_e32 v72, v214
	v_mov_b32_e32 v73, v215
	v_lshlrev_b32_e32 v76, 16, v66
	v_and_b32_e32 v77, 0xffff0000, v66
	v_lshlrev_b32_e32 v66, 16, v67
	v_and_b32_e32 v67, 0xffff0000, v67
	v_lshlrev_b32_e32 v78, 16, v68
	v_and_b32_e32 v79, 0xffff0000, v68
	v_lshlrev_b32_e32 v68, 16, v69
	v_and_b32_e32 v69, 0xffff0000, v69
	v_lshlrev_b32_e32 v80, 16, v70
	v_and_b32_e32 v81, 0xffff0000, v70
	v_lshlrev_b32_e32 v70, 16, v71
	v_and_b32_e32 v71, 0xffff0000, v71
	v_lshlrev_b32_e32 v82, 16, v72
	v_and_b32_e32 v83, 0xffff0000, v72
	v_lshlrev_b32_e32 v72, 16, v73
	v_and_b32_e32 v73, 0xffff0000, v73
	v_pk_add_f32 v[60:61], v[60:61], v[76:77]
	v_pk_add_f32 v[62:63], v[62:63], v[66:67]
	v_pk_add_f32 v[56:57], v[56:57], v[78:79]
	v_pk_add_f32 v[58:59], v[58:59], v[68:69]
	v_pk_add_f32 v[52:53], v[52:53], v[80:81]
	v_pk_add_f32 v[54:55], v[54:55], v[70:71]
	v_pk_add_f32 v[66:67], v[48:49], v[82:83]
	v_pk_add_f32 v[68:69], v[50:51], v[72:73]
	v_cvt_pk_bf16_f32 v48, v60, v61
	v_cvt_pk_bf16_f32 v49, v62, v63
	v_pk_mul_f32 v[50:51], v[60:61], v[60:61]
	v_pk_mul_f32 v[60:61], v[62:63], v[62:63]
	v_pk_mul_f32 v[62:63], v[56:57], v[56:57]
	v_pk_mul_f32 v[70:71], v[58:59], v[58:59]
	v_pk_mul_f32 v[72:73], v[52:53], v[52:53]
	v_pk_mul_f32 v[76:77], v[54:55], v[54:55]
	v_pk_mul_f32 v[78:79], v[66:67], v[66:67]
	v_pk_mul_f32 v[80:81], v[68:69], v[68:69]
	v_add_f32_e32 v78, v78, v79
	v_add_f32_e32 v80, v80, v81
	v_add_f32_e32 v76, v76, v77
	v_add_f32_e32 v72, v72, v73
	v_add_f32_e32 v70, v70, v71
	v_add_f32_e32 v62, v62, v63
	v_add_f32_e32 v60, v60, v61
	v_add_f32_e32 v50, v50, v51
	v_add_f32_e32 v51, v78, v80
	v_add_f32_e32 v61, v72, v76
	v_add_f32_e32 v62, v62, v70
	v_add_f32_e32 v50, v50, v60
	v_add_f32_e32 v51, v61, v51
	v_add_f32_e32 v50, v50, v62
	v_add_f32_e32 v60, v50, v51
	v_mov_b32_e32 v61, v60
	s_nop 1
	v_permlane16_swap_b32_e32 v60, v61
	v_cvt_pk_bf16_f32 v50, v56, v57
	v_cvt_pk_bf16_f32 v51, v58, v59
	global_store_dwordx4 v[74:75], v[48:51], off
	s_waitcnt lgkmcnt(0)
	s_nop 0
	v_add_f32_e32 v48, v60, v61
	v_mov_b32_e32 v49, v48
	s_nop 1
	v_permlane32_swap_b32_e32 v48, v49
	v_cvt_pk_bf16_f32 v50, v52, v53
	v_cvt_pk_bf16_f32 v51, v54, v55
	v_cvt_pk_bf16_f32 v52, v66, v67
	v_cvt_pk_bf16_f32 v53, v68, v69
	global_store_dwordx4 v[74:75], v[50:53], off offset:256
	s_and_saveexec_b64 s[30:31], s[4:5]
	s_cbranch_execz .LBB0_1161
	v_lshlrev_b64 v[50:51], 6, v[64:65]
	v_lshl_add_u64 v[50:51], s[14:15], 0, v[50:51]
	v_lshl_add_u64 v[50:51], s[28:29], 2, v[50:51]
	s_lshl_b32 s8, s46, 2
	v_lshl_add_u64 v[50:51], v[50:51], 0, s[8:9]
	s_waitcnt lgkmcnt(0)
	v_add_f32_e32 v48, v48, v49
	global_store_dword v[50:51], v48, off
.LBB0_1161:
	s_or_b64 exec, exec, s[30:31]
	v_add_u32_e32 v48, 0x90, v150
	s_waitcnt lgkmcnt(0)
	v_ashrrev_i32_e32 v49, 31, v48
	v_lshlrev_b64 v[50:51], 11, v[48:49]
	v_lshl_add_u64 v[50:51], s[12:13], 0, v[50:51]
	v_lshl_add_u64 v[58:59], v[148:149], 1, v[50:51]
	s_nop 1
	v_mov_b32_e32 v50, v216
	v_mov_b32_e32 v51, v217
	v_mov_b32_e32 v52, v218
	v_mov_b32_e32 v53, v219
	v_mov_b32_e32 v54, v220
	v_mov_b32_e32 v55, v221
	v_mov_b32_e32 v56, v222
	v_mov_b32_e32 v57, v223
	v_lshlrev_b32_e32 v60, 16, v50
	v_and_b32_e32 v61, 0xffff0000, v50
	v_lshlrev_b32_e32 v50, 16, v51
	v_and_b32_e32 v51, 0xffff0000, v51
	v_lshlrev_b32_e32 v62, 16, v52
	v_and_b32_e32 v63, 0xffff0000, v52
	v_lshlrev_b32_e32 v52, 16, v53
	v_and_b32_e32 v53, 0xffff0000, v53
	v_lshlrev_b32_e32 v64, 16, v54
	v_and_b32_e32 v65, 0xffff0000, v54
	v_lshlrev_b32_e32 v54, 16, v55
	v_and_b32_e32 v55, 0xffff0000, v55
	v_lshlrev_b32_e32 v66, 16, v56
	v_and_b32_e32 v67, 0xffff0000, v56
	v_lshlrev_b32_e32 v56, 16, v57
	v_and_b32_e32 v57, 0xffff0000, v57
	v_pk_add_f32 v[44:45], v[44:45], v[60:61]
	v_pk_add_f32 v[46:47], v[46:47], v[50:51]
	v_pk_add_f32 v[40:41], v[40:41], v[62:63]
	v_pk_add_f32 v[42:43], v[42:43], v[52:53]
	v_pk_add_f32 v[36:37], v[36:37], v[64:65]
	v_pk_add_f32 v[38:39], v[38:39], v[54:55]
	v_pk_add_f32 v[50:51], v[32:33], v[66:67]
	v_pk_add_f32 v[52:53], v[34:35], v[56:57]
	v_cvt_pk_bf16_f32 v32, v44, v45
	v_cvt_pk_bf16_f32 v33, v46, v47
	v_pk_mul_f32 v[34:35], v[44:45], v[44:45]
	v_pk_mul_f32 v[44:45], v[46:47], v[46:47]
	v_pk_mul_f32 v[46:47], v[40:41], v[40:41]
	v_pk_mul_f32 v[54:55], v[42:43], v[42:43]
	v_pk_mul_f32 v[56:57], v[36:37], v[36:37]
	v_pk_mul_f32 v[60:61], v[38:39], v[38:39]
	v_pk_mul_f32 v[62:63], v[50:51], v[50:51]
	v_pk_mul_f32 v[64:65], v[52:53], v[52:53]
	v_add_f32_e32 v62, v62, v63
	v_add_f32_e32 v64, v64, v65
	v_add_f32_e32 v60, v60, v61
	v_add_f32_e32 v56, v56, v57
	v_add_f32_e32 v54, v54, v55
	v_add_f32_e32 v46, v46, v47
	v_add_f32_e32 v44, v44, v45
	v_add_f32_e32 v34, v34, v35
	v_add_f32_e32 v35, v62, v64
	v_add_f32_e32 v45, v56, v60
	v_add_f32_e32 v46, v46, v54
	v_add_f32_e32 v34, v34, v44
	v_add_f32_e32 v35, v45, v35
	v_add_f32_e32 v34, v34, v46
	v_add_f32_e32 v44, v34, v35
	v_mov_b32_e32 v45, v44
	s_nop 1
	v_permlane16_swap_b32_e32 v44, v45
	v_cvt_pk_bf16_f32 v34, v40, v41
	v_cvt_pk_bf16_f32 v35, v42, v43
	global_store_dwordx4 v[58:59], v[32:35], off
	s_waitcnt lgkmcnt(0)
	s_nop 0
	v_add_f32_e32 v32, v44, v45
	v_mov_b32_e32 v33, v32
	s_nop 1
	v_permlane32_swap_b32_e32 v32, v33
	v_cvt_pk_bf16_f32 v34, v36, v37
	v_cvt_pk_bf16_f32 v35, v38, v39
	v_cvt_pk_bf16_f32 v36, v50, v51
	v_cvt_pk_bf16_f32 v37, v52, v53
	global_store_dwordx4 v[58:59], v[34:37], off offset:256
	s_and_saveexec_b64 s[30:31], s[4:5]
	s_cbranch_execz .LBB0_1163
	v_lshlrev_b64 v[34:35], 6, v[48:49]
	v_lshl_add_u64 v[34:35], s[14:15], 0, v[34:35]
	v_lshl_add_u64 v[34:35], s[28:29], 2, v[34:35]
	s_lshl_b32 s8, s46, 2
	v_lshl_add_u64 v[34:35], v[34:35], 0, s[8:9]
	s_waitcnt lgkmcnt(0)
	v_add_f32_e32 v32, v32, v33
	global_store_dword v[34:35], v32, off
.LBB0_1163:
	s_or_b64 exec, exec, s[30:31]
	v_add_u32_e32 v32, 0xa0, v150
	s_waitcnt lgkmcnt(0)
	v_ashrrev_i32_e32 v33, 31, v32
	v_lshlrev_b64 v[34:35], 11, v[32:33]
	v_lshl_add_u64 v[34:35], s[12:13], 0, v[34:35]
	v_lshl_add_u64 v[42:43], v[148:149], 1, v[34:35]
	s_nop 1
	v_mov_b32_e32 v34, v224
	v_mov_b32_e32 v35, v225
	v_mov_b32_e32 v36, v226
	v_mov_b32_e32 v37, v227
	v_mov_b32_e32 v38, v228
	v_mov_b32_e32 v39, v229
	v_mov_b32_e32 v40, v230
	v_mov_b32_e32 v41, v231
	v_lshlrev_b32_e32 v44, 16, v34
	v_and_b32_e32 v45, 0xffff0000, v34
	v_lshlrev_b32_e32 v34, 16, v35
	v_and_b32_e32 v35, 0xffff0000, v35
	v_lshlrev_b32_e32 v46, 16, v36
	v_and_b32_e32 v47, 0xffff0000, v36
	v_lshlrev_b32_e32 v36, 16, v37
	v_and_b32_e32 v37, 0xffff0000, v37
	v_lshlrev_b32_e32 v48, 16, v38
	v_and_b32_e32 v49, 0xffff0000, v38
	v_lshlrev_b32_e32 v38, 16, v39
	v_and_b32_e32 v39, 0xffff0000, v39
	v_lshlrev_b32_e32 v50, 16, v40
	v_and_b32_e32 v51, 0xffff0000, v40
	v_lshlrev_b32_e32 v40, 16, v41
	v_and_b32_e32 v41, 0xffff0000, v41
	v_pk_add_f32 v[28:29], v[28:29], v[44:45]
	v_pk_add_f32 v[30:31], v[30:31], v[34:35]
	v_pk_add_f32 v[24:25], v[24:25], v[46:47]
	v_pk_add_f32 v[26:27], v[26:27], v[36:37]
	v_pk_add_f32 v[20:21], v[20:21], v[48:49]
	v_pk_add_f32 v[22:23], v[22:23], v[38:39]
	v_pk_add_f32 v[34:35], v[16:17], v[50:51]
	v_pk_add_f32 v[36:37], v[18:19], v[40:41]
	v_cvt_pk_bf16_f32 v16, v28, v29
	v_cvt_pk_bf16_f32 v17, v30, v31
	v_pk_mul_f32 v[18:19], v[28:29], v[28:29]
	v_pk_mul_f32 v[28:29], v[30:31], v[30:31]
	v_pk_mul_f32 v[30:31], v[24:25], v[24:25]
	v_pk_mul_f32 v[38:39], v[26:27], v[26:27]
	v_pk_mul_f32 v[40:41], v[20:21], v[20:21]
	v_pk_mul_f32 v[44:45], v[22:23], v[22:23]
	v_pk_mul_f32 v[46:47], v[34:35], v[34:35]
	v_pk_mul_f32 v[48:49], v[36:37], v[36:37]
	v_add_f32_e32 v46, v46, v47
	v_add_f32_e32 v48, v48, v49
	v_add_f32_e32 v44, v44, v45
	v_add_f32_e32 v40, v40, v41
	v_add_f32_e32 v38, v38, v39
	v_add_f32_e32 v30, v30, v31
	v_add_f32_e32 v28, v28, v29
	v_add_f32_e32 v18, v18, v19
	v_add_f32_e32 v19, v46, v48
	v_add_f32_e32 v29, v40, v44
	v_add_f32_e32 v30, v30, v38
	v_add_f32_e32 v18, v18, v28
	v_add_f32_e32 v19, v29, v19
	v_add_f32_e32 v18, v18, v30
	v_add_f32_e32 v28, v18, v19
	v_mov_b32_e32 v29, v28
	s_nop 1
	v_permlane16_swap_b32_e32 v28, v29
	v_cvt_pk_bf16_f32 v18, v24, v25
	v_cvt_pk_bf16_f32 v19, v26, v27
	global_store_dwordx4 v[42:43], v[16:19], off
	s_waitcnt lgkmcnt(0)
	s_nop 0
	v_add_f32_e32 v16, v28, v29
	v_mov_b32_e32 v17, v16
	s_nop 1
	v_permlane32_swap_b32_e32 v16, v17
	v_cvt_pk_bf16_f32 v18, v20, v21
	v_cvt_pk_bf16_f32 v19, v22, v23
	v_cvt_pk_bf16_f32 v20, v34, v35
	v_cvt_pk_bf16_f32 v21, v36, v37
	global_store_dwordx4 v[42:43], v[18:21], off offset:256
	s_and_saveexec_b64 s[30:31], s[4:5]
	s_cbranch_execz .LBB0_1165
	v_lshlrev_b64 v[18:19], 6, v[32:33]
	v_lshl_add_u64 v[18:19], s[14:15], 0, v[18:19]
	v_lshl_add_u64 v[18:19], s[28:29], 2, v[18:19]
	s_lshl_b32 s8, s46, 2
	v_lshl_add_u64 v[18:19], v[18:19], 0, s[8:9]
	s_waitcnt lgkmcnt(0)
	v_add_f32_e32 v16, v16, v17
	global_store_dword v[18:19], v16, off
.LBB0_1165:
	s_or_b64 exec, exec, s[30:31]
	v_add_u32_e32 v16, 0xb0, v150
	s_waitcnt lgkmcnt(0)
	v_ashrrev_i32_e32 v17, 31, v16
	v_lshlrev_b64 v[18:19], 11, v[16:17]
	v_lshl_add_u64 v[18:19], s[12:13], 0, v[18:19]
	v_lshl_add_u64 v[26:27], v[148:149], 1, v[18:19]
	s_nop 1
	v_mov_b32_e32 v18, v238
	v_mov_b32_e32 v19, v239
	v_mov_b32_e32 v20, v240
	v_mov_b32_e32 v21, v241
	v_mov_b32_e32 v22, v242
	v_mov_b32_e32 v23, v243
	v_mov_b32_e32 v24, v244
	v_mov_b32_e32 v25, v245
	v_lshlrev_b32_e32 v28, 16, v18
	v_and_b32_e32 v29, 0xffff0000, v18
	v_lshlrev_b32_e32 v18, 16, v19
	v_and_b32_e32 v19, 0xffff0000, v19
	v_lshlrev_b32_e32 v30, 16, v20
	v_and_b32_e32 v31, 0xffff0000, v20
	v_lshlrev_b32_e32 v20, 16, v21
	v_and_b32_e32 v21, 0xffff0000, v21
	v_lshlrev_b32_e32 v32, 16, v22
	v_and_b32_e32 v33, 0xffff0000, v22
	v_lshlrev_b32_e32 v22, 16, v23
	v_and_b32_e32 v23, 0xffff0000, v23
	v_lshlrev_b32_e32 v34, 16, v24
	v_and_b32_e32 v35, 0xffff0000, v24
	v_lshlrev_b32_e32 v24, 16, v25
	v_and_b32_e32 v25, 0xffff0000, v25
	v_pk_add_f32 v[12:13], v[12:13], v[28:29]
	v_pk_add_f32 v[14:15], v[14:15], v[18:19]
	v_pk_add_f32 v[8:9], v[8:9], v[30:31]
	v_pk_add_f32 v[10:11], v[10:11], v[20:21]
	v_pk_add_f32 v[4:5], v[4:5], v[32:33]
	v_pk_add_f32 v[6:7], v[6:7], v[22:23]
	v_pk_add_f32 v[18:19], v[0:1], v[34:35]
	v_pk_add_f32 v[20:21], v[2:3], v[24:25]
	v_cvt_pk_bf16_f32 v0, v12, v13
	v_cvt_pk_bf16_f32 v1, v14, v15
	v_pk_mul_f32 v[2:3], v[12:13], v[12:13]
	v_pk_mul_f32 v[12:13], v[14:15], v[14:15]
	v_pk_mul_f32 v[14:15], v[8:9], v[8:9]
	v_pk_mul_f32 v[22:23], v[10:11], v[10:11]
	v_pk_mul_f32 v[24:25], v[4:5], v[4:5]
	v_pk_mul_f32 v[28:29], v[6:7], v[6:7]
	v_pk_mul_f32 v[30:31], v[18:19], v[18:19]
	v_pk_mul_f32 v[32:33], v[20:21], v[20:21]
	v_add_f32_e32 v30, v30, v31
	v_add_f32_e32 v32, v32, v33
	v_add_f32_e32 v28, v28, v29
	v_add_f32_e32 v24, v24, v25
	v_add_f32_e32 v22, v22, v23
	v_add_f32_e32 v14, v14, v15
	v_add_f32_e32 v12, v12, v13
	v_add_f32_e32 v2, v2, v3
	v_add_f32_e32 v3, v30, v32
	v_add_f32_e32 v13, v24, v28
	v_add_f32_e32 v14, v14, v22
	v_add_f32_e32 v2, v2, v12
	v_add_f32_e32 v3, v13, v3
	v_add_f32_e32 v2, v2, v14
	v_add_f32_e32 v12, v2, v3
	v_mov_b32_e32 v13, v12
	s_nop 1
	v_permlane16_swap_b32_e32 v12, v13
	v_cvt_pk_bf16_f32 v2, v8, v9
	v_cvt_pk_bf16_f32 v3, v10, v11
	global_store_dwordx4 v[26:27], v[0:3], off
	s_waitcnt lgkmcnt(0)
	s_nop 0
	v_add_f32_e32 v0, v12, v13
	v_mov_b32_e32 v1, v0
	s_nop 1
	v_permlane32_swap_b32_e32 v0, v1
	v_cvt_pk_bf16_f32 v2, v4, v5
	v_cvt_pk_bf16_f32 v3, v6, v7
	v_cvt_pk_bf16_f32 v4, v18, v19
	v_cvt_pk_bf16_f32 v5, v20, v21
	global_store_dwordx4 v[26:27], v[2:5], off offset:256
	s_and_saveexec_b64 s[30:31], s[4:5]
	s_cbranch_execz .LBB0_1167
	v_lshlrev_b64 v[2:3], 6, v[16:17]
	v_lshl_add_u64 v[2:3], s[14:15], 0, v[2:3]
	v_lshl_add_u64 v[2:3], s[28:29], 2, v[2:3]
	s_lshl_b32 s8, s46, 2
	v_lshl_add_u64 v[2:3], v[2:3], 0, s[8:9]
	s_waitcnt lgkmcnt(0)
	v_add_f32_e32 v0, v0, v1
	global_store_dword v[2:3], v0, off

.LBB0_1238:
	v_lshl_add_u32 v152, s0, 8, v131
	v_ashrrev_i32_e32 v153, 31, v152
	v_lshlrev_b64 v[150:151], 6, v[152:153]
	v_lshl_add_u64 v[150:151], v[140:141], 0, v[150:151]
	global_load_dwordx4 v[162:165], v[150:151], off
	global_load_dwordx4 v[188:191], v[150:151], off offset:1024
	global_load_dwordx4 v[192:195], v[150:151], off offset:2048
	global_load_dwordx4 v[196:199], v[150:151], off offset:3072
	v_mov_b32_e32 v216, 0x2000
	v_mov_b32_e32 v217, 0
	v_lshl_add_u64 v[216:217], v[150:151], 0, v[216:217]
	global_load_dwordx4 v[200:203], v[216:217], off
	global_load_dwordx4 v[204:207], v[216:217], off offset:1024
	global_load_dwordx4 v[208:211], v[216:217], off offset:2048
	global_load_dwordx4 v[212:215], v[216:217], off offset:3072
	v_and_b32_e32 v161, 64, v159
	v_xor_b32_e32 v153, 16, v159
	v_pk_mul_f32 v[168:169], v[114:115], v[122:123]
	v_add_u32_e32 v122, 64, v161
	v_cmp_lt_i32_e32 vcc, v153, v122
	v_pk_mul_f32 v[170:171], v[112:113], v[120:121]
	v_xor_b32_e32 v172, 32, v159
	v_cndmask_b32_e32 v120, v159, v153, vcc
	v_lshlrev_b32_e32 v123, 2, v120
	v_cmp_lt_i32_e32 vcc, v172, v122
	v_pk_mul_f32 v[126:127], v[118:119], v[126:127]
	v_pk_mul_f32 v[124:125], v[116:117], v[124:125]
	v_cndmask_b32_e32 v122, v159, v172, vcc
	v_lshlrev_b32_e32 v122, 2, v122
	v_lshl_or_b32 v166, s1, 7, v155
	v_ashrrev_i32_e32 v167, 31, v166
	v_mov_b64_e32 v[150:151], s[10:11]
	v_pk_mul_f32 v[110:111], v[102:103], v[110:111]
	v_pk_mul_f32 v[108:109], v[100:101], v[108:109]
	v_pk_mul_f32 v[106:107], v[98:99], v[106:107]
	v_pk_mul_f32 v[104:105], v[96:97], v[104:105]
	v_pk_mul_f32 v[94:95], v[86:87], v[94:95]
	v_pk_mul_f32 v[92:93], v[84:85], v[92:93]
	v_pk_mul_f32 v[90:91], v[82:83], v[90:91]
	v_pk_mul_f32 v[88:89], v[80:81], v[88:89]
	v_pk_mul_f32 v[78:79], v[70:71], v[78:79]
	v_pk_mul_f32 v[76:77], v[68:69], v[76:77]
	v_pk_mul_f32 v[74:75], v[66:67], v[74:75]
	v_pk_mul_f32 v[72:73], v[64:65], v[72:73]
	v_pk_mul_f32 v[62:63], v[54:55], v[62:63]
	v_pk_mul_f32 v[60:61], v[52:53], v[60:61]
	v_pk_mul_f32 v[58:59], v[50:51], v[58:59]
	v_pk_mul_f32 v[56:57], v[48:49], v[56:57]
	v_pk_mul_f32 v[46:47], v[38:39], v[46:47]
	v_pk_mul_f32 v[44:45], v[36:37], v[44:45]
	v_pk_mul_f32 v[42:43], v[34:35], v[42:43]
	v_pk_mul_f32 v[40:41], v[32:33], v[40:41]
	v_pk_mul_f32 v[30:31], v[22:23], v[30:31]
	v_pk_mul_f32 v[28:29], v[20:21], v[28:29]
	v_pk_mul_f32 v[26:27], v[18:19], v[26:27]
	v_pk_mul_f32 v[24:25], v[16:17], v[24:25]
	v_pk_mul_f32 v[14:15], v[6:7], v[14:15]
	v_pk_mul_f32 v[12:13], v[4:5], v[12:13]
	v_pk_mul_f32 v[10:11], v[2:3], v[10:11]
	v_pk_mul_f32 v[8:9], v[0:1], v[8:9]
	s_waitcnt vmcnt(0)
	v_mov_b32_e32 v120, v163
	v_mov_b32_e32 v121, v164
	v_mov_b32_e32 v163, v165
	v_pk_add_f32 v[120:121], v[120:121], v[162:163]
	v_or_b32_e32 v164, 16, v152
	v_add_f32_e32 v120, v120, v121
	v_mov_b32_e32 v121, v120
	s_nop 1
	v_permlane16_swap_b32_e32 v120, v121
	v_ashrrev_i32_e32 v165, 31, v164
	v_mad_i64_i32 v[162:163], s[0:1], v152, s49, v[150:151]
	s_waitcnt lgkmcnt(0)
	v_add_f32_e32 v153, v120, v121
	v_mov_b32_e32 v161, v153
	s_nop 1
	v_permlane32_swap_b32_e32 v153, v161
	v_lshlrev_b64 v[120:121], 1, v[166:167]
	v_lshlrev_b64 v[166:167], 6, v[164:165]
	v_lshl_add_u64 v[162:163], v[162:163], 0, v[120:121]
	v_lshl_add_u64 v[166:167], v[140:141], 0, v[166:167]
	s_waitcnt lgkmcnt(0)
	v_add_f32_e32 v153, v153, v161
	v_fmamk_f32 v153, v153, 0x3a800000, v160
	v_mul_f32_e32 v161, 0x4b800000, v153
	v_cmp_gt_f32_e32 vcc, s52, v153
	s_nop 1
	v_cndmask_b32_e32 v153, v153, v161, vcc
	v_rsq_f32_e32 v153, v153
	s_nop 0
	v_mul_f32_e32 v161, 0x45800000, v153
	v_cndmask_b32_e32 v153, v153, v161, vcc
	v_mul_f32_e32 v161, 0xbfb8aa3b, v153
	v_mul_f32_e32 v116, v116, v161
	v_mul_f32_e32 v117, v117, v161
	v_mul_f32_e32 v118, v118, v161
	v_mul_f32_e32 v119, v119, v161
	v_mul_f32_e32 v112, v112, v161
	v_mul_f32_e32 v113, v113, v161
	v_mul_f32_e32 v114, v114, v161
	v_mul_f32_e32 v115, v115, v161
	v_exp_f32_e32 v116, v116
	v_exp_f32_e32 v117, v117
	v_exp_f32_e32 v118, v118
	v_exp_f32_e32 v119, v119
	v_exp_f32_e32 v112, v112
	v_exp_f32_e32 v113, v113
	v_exp_f32_e32 v114, v114
	v_exp_f32_e32 v115, v115
	v_mul_f32_e32 v172, v153, v153
	v_add_f32_e32 v116, 1.0, v116
	v_add_f32_e32 v117, 1.0, v117
	v_add_f32_e32 v118, 1.0, v118
	v_add_f32_e32 v119, 1.0, v119
	v_add_f32_e32 v153, 1.0, v112
	v_add_f32_e32 v161, 1.0, v113
	v_add_f32_e32 v165, 1.0, v114
	v_add_f32_e32 v173, 1.0, v115
	v_rcp_f32_e32 v112, v116
	v_rcp_f32_e32 v113, v117
	v_rcp_f32_e32 v114, v118
	v_rcp_f32_e32 v115, v119
	v_rcp_f32_e32 v116, v153
	v_rcp_f32_e32 v117, v161
	v_rcp_f32_e32 v118, v165
	v_rcp_f32_e32 v119, v173
	v_pk_mul_f32 v[112:113], v[172:173], v[112:113] op_sel_hi:[0,1]
	v_pk_mul_f32 v[114:115], v[172:173], v[114:115] op_sel_hi:[0,1]
	v_pk_mul_f32 v[116:117], v[172:173], v[116:117] op_sel_hi:[0,1]
	v_pk_mul_f32 v[118:119], v[172:173], v[118:119] op_sel_hi:[0,1]
	v_pk_mul_f32 v[112:113], v[124:125], v[112:113]
	v_pk_mul_f32 v[114:115], v[126:127], v[114:115]
	v_pk_mul_f32 v[116:117], v[170:171], v[116:117]
	v_pk_mul_f32 v[118:119], v[168:169], v[118:119]
	v_cvt_pk_bf16_f32 v112, v112, v113
	v_cvt_pk_bf16_f32 v113, v114, v115
	v_cvt_pk_bf16_f32 v114, v116, v117
	v_cvt_pk_bf16_f32 v115, v118, v119
	global_store_dwordx4 v[162:163], v[112:115], off
	s_nop 1
	v_mov_b32_e32 v112, v188
	v_mov_b32_e32 v113, v189
	v_mov_b32_e32 v114, v190
	v_mov_b32_e32 v115, v191
	v_mov_b32_e32 v116, v113
	v_mov_b32_e32 v117, v114
	v_mov_b32_e32 v113, v115
	v_pk_add_f32 v[112:113], v[116:117], v[112:113]
	v_mad_i64_i32 v[114:115], s[0:1], v164, s49, v[150:151]
	v_add_f32_e32 v112, v112, v113
	v_mov_b32_e32 v113, v112
	s_nop 1
	v_permlane16_swap_b32_e32 v112, v113
	v_lshl_add_u64 v[114:115], v[114:115], 0, v[120:121]
	s_waitcnt lgkmcnt(0)
	v_add_f32_e32 v116, v112, v113
	v_mov_b32_e32 v117, v116
	s_nop 1
	v_permlane32_swap_b32_e32 v116, v117
	v_or_b32_e32 v112, 32, v152
	v_ashrrev_i32_e32 v113, 31, v112
	s_waitcnt lgkmcnt(0)
	v_add_f32_e32 v116, v116, v117
	v_fmamk_f32 v116, v116, 0x3a800000, v160
	v_mul_f32_e32 v117, 0x4b800000, v116
	v_cmp_gt_f32_e32 vcc, s52, v116
	s_nop 1
	v_cndmask_b32_e32 v116, v116, v117, vcc
	v_rsq_f32_e32 v118, v116
	v_lshlrev_b64 v[116:117], 6, v[112:113]
	v_lshl_add_u64 v[116:117], v[140:141], 0, v[116:117]
	v_mul_f32_e32 v113, 0x45800000, v118
	v_cndmask_b32_e32 v113, v118, v113, vcc
	v_mul_f32_e32 v119, 0xbfb8aa3b, v113
	v_mul_f32_e32 v100, v100, v119
	v_mul_f32_e32 v101, v101, v119
	v_mul_f32_e32 v102, v102, v119
	v_mul_f32_e32 v103, v103, v119
	v_mul_f32_e32 v96, v96, v119
	v_mul_f32_e32 v97, v97, v119
	v_mul_f32_e32 v98, v98, v119
	v_mul_f32_e32 v99, v99, v119
	v_exp_f32_e32 v100, v100
	v_exp_f32_e32 v101, v101
	v_exp_f32_e32 v102, v102
	v_exp_f32_e32 v103, v103
	v_exp_f32_e32 v96, v96
	v_exp_f32_e32 v97, v97
	v_exp_f32_e32 v98, v98
	v_exp_f32_e32 v99, v99
	v_mul_f32_e32 v118, v113, v113
	v_add_f32_e32 v100, 1.0, v100
	v_add_f32_e32 v101, 1.0, v101
	v_add_f32_e32 v102, 1.0, v102
	v_add_f32_e32 v103, 1.0, v103
	v_add_f32_e32 v113, 1.0, v96
	v_add_f32_e32 v119, 1.0, v97
	v_add_f32_e32 v124, 1.0, v98
	v_add_f32_e32 v125, 1.0, v99
	v_rcp_f32_e32 v96, v100
	v_rcp_f32_e32 v97, v101
	v_rcp_f32_e32 v98, v102
	v_rcp_f32_e32 v99, v103
	v_rcp_f32_e32 v100, v113
	v_rcp_f32_e32 v101, v119
	v_rcp_f32_e32 v102, v124
	v_rcp_f32_e32 v103, v125
	v_pk_mul_f32 v[96:97], v[118:119], v[96:97] op_sel_hi:[0,1]
	v_pk_mul_f32 v[98:99], v[118:119], v[98:99] op_sel_hi:[0,1]
	v_pk_mul_f32 v[100:101], v[118:119], v[100:101] op_sel_hi:[0,1]
	v_pk_mul_f32 v[102:103], v[118:119], v[102:103] op_sel_hi:[0,1]
	v_pk_mul_f32 v[96:97], v[108:109], v[96:97]
	v_pk_mul_f32 v[98:99], v[110:111], v[98:99]
	v_pk_mul_f32 v[100:101], v[104:105], v[100:101]
	v_pk_mul_f32 v[102:103], v[106:107], v[102:103]
	v_cvt_pk_bf16_f32 v96, v96, v97
	v_cvt_pk_bf16_f32 v97, v98, v99
	v_cvt_pk_bf16_f32 v98, v100, v101
	v_cvt_pk_bf16_f32 v99, v102, v103
	global_store_dwordx4 v[114:115], v[96:99], off
	s_nop 1
	v_mov_b32_e32 v96, v192
	v_mov_b32_e32 v97, v193
	v_mov_b32_e32 v98, v194
	v_mov_b32_e32 v99, v195
	v_mov_b32_e32 v100, v97
	v_mov_b32_e32 v101, v98
	v_mov_b32_e32 v97, v99
	v_pk_add_f32 v[96:97], v[100:101], v[96:97]
	v_mad_i64_i32 v[98:99], s[0:1], v112, s49, v[150:151]
	v_add_f32_e32 v96, v96, v97
	v_mov_b32_e32 v97, v96
	s_nop 1
	v_permlane16_swap_b32_e32 v96, v97
	v_lshl_add_u64 v[98:99], v[98:99], 0, v[120:121]
	s_waitcnt lgkmcnt(0)
	v_add_f32_e32 v100, v96, v97
	v_mov_b32_e32 v101, v100
	s_nop 1
	v_permlane32_swap_b32_e32 v100, v101
	v_or_b32_e32 v96, 48, v152
	v_ashrrev_i32_e32 v97, 31, v96
	s_waitcnt lgkmcnt(0)
	v_add_f32_e32 v100, v100, v101
	v_fmamk_f32 v100, v100, 0x3a800000, v160
	v_mul_f32_e32 v101, 0x4b800000, v100
	v_cmp_gt_f32_e32 vcc, s52, v100
	s_nop 1
	v_cndmask_b32_e32 v100, v100, v101, vcc
	v_rsq_f32_e32 v102, v100
	v_lshlrev_b64 v[100:101], 6, v[96:97]
	v_lshl_add_u64 v[100:101], v[140:141], 0, v[100:101]
	v_mul_f32_e32 v97, 0x45800000, v102
	v_cndmask_b32_e32 v97, v102, v97, vcc
	v_mul_f32_e32 v103, 0xbfb8aa3b, v97
	v_mul_f32_e32 v84, v84, v103
	v_mul_f32_e32 v85, v85, v103
	v_mul_f32_e32 v86, v86, v103
	v_mul_f32_e32 v87, v87, v103
	v_mul_f32_e32 v80, v80, v103
	v_mul_f32_e32 v81, v81, v103
	v_mul_f32_e32 v82, v82, v103
	v_mul_f32_e32 v83, v83, v103
	v_exp_f32_e32 v84, v84
	v_exp_f32_e32 v85, v85
	v_exp_f32_e32 v86, v86
	v_exp_f32_e32 v87, v87
	v_exp_f32_e32 v80, v80
	v_exp_f32_e32 v81, v81
	v_exp_f32_e32 v82, v82
	v_exp_f32_e32 v83, v83
	v_mul_f32_e32 v102, v97, v97
	v_add_f32_e32 v84, 1.0, v84
	v_add_f32_e32 v85, 1.0, v85
	v_add_f32_e32 v86, 1.0, v86
	v_add_f32_e32 v87, 1.0, v87
	v_add_f32_e32 v97, 1.0, v80
	v_add_f32_e32 v103, 1.0, v81
	v_add_f32_e32 v104, 1.0, v82
	v_add_f32_e32 v105, 1.0, v83
	v_rcp_f32_e32 v80, v84
	v_rcp_f32_e32 v81, v85
	v_rcp_f32_e32 v82, v86
	v_rcp_f32_e32 v83, v87
	v_rcp_f32_e32 v84, v97
	v_rcp_f32_e32 v85, v103
	v_rcp_f32_e32 v86, v104
	v_rcp_f32_e32 v87, v105
	v_pk_mul_f32 v[80:81], v[102:103], v[80:81] op_sel_hi:[0,1]
	v_pk_mul_f32 v[82:83], v[102:103], v[82:83] op_sel_hi:[0,1]
	v_pk_mul_f32 v[84:85], v[102:103], v[84:85] op_sel_hi:[0,1]
	v_pk_mul_f32 v[86:87], v[102:103], v[86:87] op_sel_hi:[0,1]
	v_pk_mul_f32 v[80:81], v[92:93], v[80:81]
	v_pk_mul_f32 v[82:83], v[94:95], v[82:83]
	v_pk_mul_f32 v[84:85], v[88:89], v[84:85]
	v_pk_mul_f32 v[86:87], v[90:91], v[86:87]
	v_cvt_pk_bf16_f32 v80, v80, v81
	v_cvt_pk_bf16_f32 v81, v82, v83
	v_cvt_pk_bf16_f32 v82, v84, v85
	v_cvt_pk_bf16_f32 v83, v86, v87
	global_store_dwordx4 v[98:99], v[80:83], off
	s_nop 1
	v_mov_b32_e32 v80, v196
	v_mov_b32_e32 v81, v197
	v_mov_b32_e32 v82, v198
	v_mov_b32_e32 v83, v199
	v_mov_b32_e32 v84, v81
	v_mov_b32_e32 v85, v82
	v_mov_b32_e32 v81, v83
	v_pk_add_f32 v[80:81], v[84:85], v[80:81]
	v_mad_i64_i32 v[82:83], s[0:1], v96, s49, v[150:151]
	v_add_f32_e32 v80, v80, v81
	v_mov_b32_e32 v81, v80
	s_nop 1
	v_permlane16_swap_b32_e32 v80, v81
	v_lshl_add_u64 v[82:83], v[82:83], 0, v[120:121]
	s_waitcnt lgkmcnt(0)
	v_add_f32_e32 v84, v80, v81
	v_mov_b32_e32 v85, v84
	s_nop 1
	v_permlane32_swap_b32_e32 v84, v85
	v_add_u32_e32 v80, 0x80, v152
	v_ashrrev_i32_e32 v81, 31, v80
	s_waitcnt lgkmcnt(0)
	v_add_f32_e32 v84, v84, v85
	v_fmamk_f32 v84, v84, 0x3a800000, v160
	v_mul_f32_e32 v85, 0x4b800000, v84
	v_cmp_gt_f32_e32 vcc, s52, v84
	s_nop 1
	v_cndmask_b32_e32 v84, v84, v85, vcc
	v_rsq_f32_e32 v86, v84
	v_lshlrev_b64 v[84:85], 6, v[80:81]
	v_lshl_add_u64 v[84:85], v[140:141], 0, v[84:85]
	v_mul_f32_e32 v81, 0x45800000, v86
	v_cndmask_b32_e32 v81, v86, v81, vcc
	v_mul_f32_e32 v87, 0xbfb8aa3b, v81
	v_mul_f32_e32 v68, v68, v87
	v_mul_f32_e32 v69, v69, v87
	v_mul_f32_e32 v70, v70, v87
	v_mul_f32_e32 v71, v71, v87
	v_mul_f32_e32 v64, v64, v87
	v_mul_f32_e32 v65, v65, v87
	v_mul_f32_e32 v66, v66, v87
	v_mul_f32_e32 v67, v67, v87
	v_exp_f32_e32 v68, v68
	v_exp_f32_e32 v69, v69
	v_exp_f32_e32 v70, v70
	v_exp_f32_e32 v71, v71
	v_exp_f32_e32 v64, v64
	v_exp_f32_e32 v65, v65
	v_exp_f32_e32 v66, v66
	v_exp_f32_e32 v67, v67
	v_mul_f32_e32 v86, v81, v81
	v_add_f32_e32 v68, 1.0, v68
	v_add_f32_e32 v69, 1.0, v69
	v_add_f32_e32 v70, 1.0, v70
	v_add_f32_e32 v71, 1.0, v71
	v_add_f32_e32 v81, 1.0, v64
	v_add_f32_e32 v87, 1.0, v65
	v_add_f32_e32 v88, 1.0, v66
	v_add_f32_e32 v89, 1.0, v67
	v_rcp_f32_e32 v64, v68
	v_rcp_f32_e32 v65, v69
	v_rcp_f32_e32 v66, v70
	v_rcp_f32_e32 v67, v71
	v_rcp_f32_e32 v68, v81
	v_rcp_f32_e32 v69, v87
	v_rcp_f32_e32 v70, v88
	v_rcp_f32_e32 v71, v89
	v_pk_mul_f32 v[64:65], v[86:87], v[64:65] op_sel_hi:[0,1]
	v_pk_mul_f32 v[66:67], v[86:87], v[66:67] op_sel_hi:[0,1]
	v_pk_mul_f32 v[68:69], v[86:87], v[68:69] op_sel_hi:[0,1]
	v_pk_mul_f32 v[70:71], v[86:87], v[70:71] op_sel_hi:[0,1]
	v_pk_mul_f32 v[64:65], v[76:77], v[64:65]
	v_pk_mul_f32 v[66:67], v[78:79], v[66:67]
	v_pk_mul_f32 v[68:69], v[72:73], v[68:69]
	v_pk_mul_f32 v[70:71], v[74:75], v[70:71]
	v_cvt_pk_bf16_f32 v64, v64, v65
	v_cvt_pk_bf16_f32 v65, v66, v67
	v_cvt_pk_bf16_f32 v66, v68, v69
	v_cvt_pk_bf16_f32 v67, v70, v71
	global_store_dwordx4 v[82:83], v[64:67], off
	s_nop 1
	v_mov_b32_e32 v64, v200
	v_mov_b32_e32 v65, v201
	v_mov_b32_e32 v66, v202
	v_mov_b32_e32 v67, v203
	v_mov_b32_e32 v68, v65
	v_mov_b32_e32 v69, v66
	v_mov_b32_e32 v65, v67
	v_pk_add_f32 v[64:65], v[68:69], v[64:65]
	v_mad_i64_i32 v[66:67], s[0:1], v80, s49, v[150:151]
	v_add_f32_e32 v64, v64, v65
	v_mov_b32_e32 v65, v64
	s_nop 1
	v_permlane16_swap_b32_e32 v64, v65
	v_lshl_add_u64 v[66:67], v[66:67], 0, v[120:121]
	s_waitcnt lgkmcnt(0)
	v_add_f32_e32 v68, v64, v65
	v_mov_b32_e32 v69, v68
	s_nop 1
	v_permlane32_swap_b32_e32 v68, v69
	v_add_u32_e32 v64, 0x90, v152
	v_ashrrev_i32_e32 v65, 31, v64
	s_waitcnt lgkmcnt(0)
	v_add_f32_e32 v68, v68, v69
	v_fmamk_f32 v68, v68, 0x3a800000, v160
	v_mul_f32_e32 v69, 0x4b800000, v68
	v_cmp_gt_f32_e32 vcc, s52, v68
	s_nop 1
	v_cndmask_b32_e32 v68, v68, v69, vcc
	v_rsq_f32_e32 v70, v68
	v_lshlrev_b64 v[68:69], 6, v[64:65]
	v_lshl_add_u64 v[68:69], v[140:141], 0, v[68:69]
	v_mul_f32_e32 v65, 0x45800000, v70
	v_cndmask_b32_e32 v65, v70, v65, vcc
	v_mul_f32_e32 v71, 0xbfb8aa3b, v65
	v_mul_f32_e32 v52, v52, v71
	v_mul_f32_e32 v53, v53, v71
	v_mul_f32_e32 v54, v54, v71
	v_mul_f32_e32 v55, v55, v71
	v_mul_f32_e32 v48, v48, v71
	v_mul_f32_e32 v49, v49, v71
	v_mul_f32_e32 v50, v50, v71
	v_mul_f32_e32 v51, v51, v71
	v_exp_f32_e32 v52, v52
	v_exp_f32_e32 v53, v53
	v_exp_f32_e32 v54, v54
	v_exp_f32_e32 v55, v55
	v_exp_f32_e32 v48, v48
	v_exp_f32_e32 v49, v49
	v_exp_f32_e32 v50, v50
	v_exp_f32_e32 v51, v51
	v_mul_f32_e32 v70, v65, v65
	v_add_f32_e32 v52, 1.0, v52
	v_add_f32_e32 v53, 1.0, v53
	v_add_f32_e32 v54, 1.0, v54
	v_add_f32_e32 v55, 1.0, v55
	v_add_f32_e32 v65, 1.0, v48
	v_add_f32_e32 v71, 1.0, v49
	v_add_f32_e32 v72, 1.0, v50
	v_add_f32_e32 v73, 1.0, v51
	v_rcp_f32_e32 v48, v52
	v_rcp_f32_e32 v49, v53
	v_rcp_f32_e32 v50, v54
	v_rcp_f32_e32 v51, v55
	v_rcp_f32_e32 v52, v65
	v_rcp_f32_e32 v53, v71
	v_rcp_f32_e32 v54, v72
	v_rcp_f32_e32 v55, v73
	v_pk_mul_f32 v[48:49], v[70:71], v[48:49] op_sel_hi:[0,1]
	v_pk_mul_f32 v[50:51], v[70:71], v[50:51] op_sel_hi:[0,1]
	v_pk_mul_f32 v[52:53], v[70:71], v[52:53] op_sel_hi:[0,1]
	v_pk_mul_f32 v[54:55], v[70:71], v[54:55] op_sel_hi:[0,1]
	v_pk_mul_f32 v[48:49], v[60:61], v[48:49]
	v_pk_mul_f32 v[50:51], v[62:63], v[50:51]
	v_pk_mul_f32 v[52:53], v[56:57], v[52:53]
	v_pk_mul_f32 v[54:55], v[58:59], v[54:55]
	v_cvt_pk_bf16_f32 v48, v48, v49
	v_cvt_pk_bf16_f32 v49, v50, v51
	v_cvt_pk_bf16_f32 v50, v52, v53
	v_cvt_pk_bf16_f32 v51, v54, v55
	global_store_dwordx4 v[66:67], v[48:51], off
	s_nop 1
	v_mov_b32_e32 v48, v204
	v_mov_b32_e32 v49, v205
	v_mov_b32_e32 v50, v206
	v_mov_b32_e32 v51, v207
	v_mov_b32_e32 v52, v49
	v_mov_b32_e32 v53, v50
	v_mov_b32_e32 v49, v51
	v_pk_add_f32 v[48:49], v[52:53], v[48:49]
	v_mad_i64_i32 v[50:51], s[0:1], v64, s49, v[150:151]
	v_add_f32_e32 v48, v48, v49
	v_mov_b32_e32 v49, v48
	s_nop 1
	v_permlane16_swap_b32_e32 v48, v49
	v_lshl_add_u64 v[50:51], v[50:51], 0, v[120:121]
	s_waitcnt lgkmcnt(0)
	v_add_f32_e32 v52, v48, v49
	v_mov_b32_e32 v53, v52
	s_nop 1
	v_permlane32_swap_b32_e32 v52, v53
	v_add_u32_e32 v48, 0xa0, v152
	v_ashrrev_i32_e32 v49, 31, v48
	s_waitcnt lgkmcnt(0)
	v_add_f32_e32 v52, v52, v53
	v_fmamk_f32 v52, v52, 0x3a800000, v160
	v_mul_f32_e32 v53, 0x4b800000, v52
	v_cmp_gt_f32_e32 vcc, s52, v52
	s_nop 1
	v_cndmask_b32_e32 v52, v52, v53, vcc
	v_rsq_f32_e32 v54, v52
	v_lshlrev_b64 v[52:53], 6, v[48:49]
	v_lshl_add_u64 v[52:53], v[140:141], 0, v[52:53]
	v_mul_f32_e32 v49, 0x45800000, v54
	v_cndmask_b32_e32 v49, v54, v49, vcc
	v_mul_f32_e32 v55, 0xbfb8aa3b, v49
	v_mul_f32_e32 v36, v36, v55
	v_mul_f32_e32 v37, v37, v55
	v_mul_f32_e32 v38, v38, v55
	v_mul_f32_e32 v39, v39, v55
	v_mul_f32_e32 v32, v32, v55
	v_mul_f32_e32 v33, v33, v55
	v_mul_f32_e32 v34, v34, v55
	v_mul_f32_e32 v35, v35, v55
	v_exp_f32_e32 v36, v36
	v_exp_f32_e32 v37, v37
	v_exp_f32_e32 v38, v38
	v_exp_f32_e32 v39, v39
	v_exp_f32_e32 v32, v32
	v_exp_f32_e32 v33, v33
	v_exp_f32_e32 v34, v34
	v_exp_f32_e32 v35, v35
	v_mul_f32_e32 v54, v49, v49
	v_add_f32_e32 v36, 1.0, v36
	v_add_f32_e32 v37, 1.0, v37
	v_add_f32_e32 v38, 1.0, v38
	v_add_f32_e32 v39, 1.0, v39
	v_add_f32_e32 v49, 1.0, v32
	v_add_f32_e32 v55, 1.0, v33
	v_add_f32_e32 v56, 1.0, v34
	v_add_f32_e32 v57, 1.0, v35
	v_rcp_f32_e32 v32, v36
	v_rcp_f32_e32 v33, v37
	v_rcp_f32_e32 v34, v38
	v_rcp_f32_e32 v35, v39
	v_rcp_f32_e32 v36, v49
	v_rcp_f32_e32 v37, v55
	v_rcp_f32_e32 v38, v56
	v_rcp_f32_e32 v39, v57
	v_pk_mul_f32 v[32:33], v[54:55], v[32:33] op_sel_hi:[0,1]
	v_pk_mul_f32 v[34:35], v[54:55], v[34:35] op_sel_hi:[0,1]
	v_pk_mul_f32 v[36:37], v[54:55], v[36:37] op_sel_hi:[0,1]
	v_pk_mul_f32 v[38:39], v[54:55], v[38:39] op_sel_hi:[0,1]
	v_pk_mul_f32 v[32:33], v[44:45], v[32:33]
	v_pk_mul_f32 v[34:35], v[46:47], v[34:35]
	v_pk_mul_f32 v[36:37], v[40:41], v[36:37]
	v_pk_mul_f32 v[38:39], v[42:43], v[38:39]
	v_cvt_pk_bf16_f32 v32, v32, v33
	v_cvt_pk_bf16_f32 v33, v34, v35
	v_cvt_pk_bf16_f32 v34, v36, v37
	v_cvt_pk_bf16_f32 v35, v38, v39
	global_store_dwordx4 v[50:51], v[32:35], off
	s_nop 1
	v_mov_b32_e32 v32, v208
	v_mov_b32_e32 v33, v209
	v_mov_b32_e32 v34, v210
	v_mov_b32_e32 v35, v211
	v_mov_b32_e32 v36, v33
	v_mov_b32_e32 v37, v34
	v_mov_b32_e32 v33, v35
	v_pk_add_f32 v[32:33], v[36:37], v[32:33]
	v_mad_i64_i32 v[34:35], s[0:1], v48, s49, v[150:151]
	v_add_f32_e32 v32, v32, v33
	v_mov_b32_e32 v33, v32
	s_nop 1
	v_permlane16_swap_b32_e32 v32, v33
	v_lshl_add_u64 v[34:35], v[34:35], 0, v[120:121]
	s_waitcnt lgkmcnt(0)
	v_add_f32_e32 v36, v32, v33
	v_mov_b32_e32 v37, v36
	s_nop 1
	v_permlane32_swap_b32_e32 v36, v37
	v_add_u32_e32 v32, 0xb0, v152
	v_ashrrev_i32_e32 v33, 31, v32
	s_waitcnt lgkmcnt(0)
	v_add_f32_e32 v36, v36, v37
	v_fmamk_f32 v36, v36, 0x3a800000, v160
	v_mul_f32_e32 v37, 0x4b800000, v36
	v_cmp_gt_f32_e32 vcc, s52, v36
	s_nop 1
	v_cndmask_b32_e32 v36, v36, v37, vcc
	v_rsq_f32_e32 v38, v36
	v_lshlrev_b64 v[36:37], 6, v[32:33]
	v_lshl_add_u64 v[36:37], v[140:141], 0, v[36:37]
	v_mul_f32_e32 v33, 0x45800000, v38
	v_cndmask_b32_e32 v33, v38, v33, vcc
	v_mul_f32_e32 v39, 0xbfb8aa3b, v33
	v_mul_f32_e32 v20, v20, v39
	v_mul_f32_e32 v21, v21, v39
	v_mul_f32_e32 v22, v22, v39
	v_mul_f32_e32 v23, v23, v39
	v_mul_f32_e32 v16, v16, v39
	v_mul_f32_e32 v17, v17, v39
	v_mul_f32_e32 v18, v18, v39
	v_mul_f32_e32 v19, v19, v39
	v_exp_f32_e32 v20, v20
	v_exp_f32_e32 v21, v21
	v_exp_f32_e32 v22, v22
	v_exp_f32_e32 v23, v23
	v_exp_f32_e32 v16, v16
	v_exp_f32_e32 v17, v17
	v_exp_f32_e32 v18, v18
	v_exp_f32_e32 v19, v19
	v_mul_f32_e32 v38, v33, v33
	v_add_f32_e32 v20, 1.0, v20
	v_add_f32_e32 v21, 1.0, v21
	v_add_f32_e32 v22, 1.0, v22
	v_add_f32_e32 v23, 1.0, v23
	v_add_f32_e32 v33, 1.0, v16
	v_add_f32_e32 v39, 1.0, v17
	v_add_f32_e32 v40, 1.0, v18
	v_add_f32_e32 v41, 1.0, v19
	v_rcp_f32_e32 v16, v20
	v_rcp_f32_e32 v17, v21
	v_rcp_f32_e32 v18, v22
	v_rcp_f32_e32 v19, v23
	v_rcp_f32_e32 v20, v33
	v_rcp_f32_e32 v21, v39
	v_rcp_f32_e32 v22, v40
	v_rcp_f32_e32 v23, v41
	v_pk_mul_f32 v[16:17], v[38:39], v[16:17] op_sel_hi:[0,1]
	v_pk_mul_f32 v[18:19], v[38:39], v[18:19] op_sel_hi:[0,1]
	v_pk_mul_f32 v[20:21], v[38:39], v[20:21] op_sel_hi:[0,1]
	v_pk_mul_f32 v[22:23], v[38:39], v[22:23] op_sel_hi:[0,1]
	v_pk_mul_f32 v[16:17], v[28:29], v[16:17]
	v_pk_mul_f32 v[18:19], v[30:31], v[18:19]
	v_pk_mul_f32 v[20:21], v[24:25], v[20:21]
	v_pk_mul_f32 v[22:23], v[26:27], v[22:23]
	v_cvt_pk_bf16_f32 v16, v16, v17
	v_cvt_pk_bf16_f32 v17, v18, v19
	v_cvt_pk_bf16_f32 v18, v20, v21
	v_cvt_pk_bf16_f32 v19, v22, v23
	global_store_dwordx4 v[34:35], v[16:19], off
	s_andn2_b64 vcc, exec, s[4:5]
	s_nop 1
	v_mov_b32_e32 v16, v212
	v_mov_b32_e32 v17, v213
	v_mov_b32_e32 v18, v214
	v_mov_b32_e32 v19, v215
	v_mov_b32_e32 v20, v17
	v_mov_b32_e32 v21, v18
	v_mov_b32_e32 v17, v19
	v_pk_add_f32 v[16:17], v[20:21], v[16:17]
	s_nop 0
	v_add_f32_e32 v16, v16, v17
	v_mov_b32_e32 v17, v16
	s_nop 1
	v_permlane16_swap_b32_e32 v16, v17
	s_waitcnt lgkmcnt(0)
	v_add_f32_e32 v16, v16, v17
	v_mov_b32_e32 v17, v16
	s_nop 1
	v_permlane32_swap_b32_e32 v16, v17
	s_waitcnt lgkmcnt(0)
	v_add_f32_e32 v16, v16, v17
	v_fmamk_f32 v16, v16, 0x3a800000, v160
	v_mul_f32_e32 v17, 0x4b800000, v16
	v_cmp_gt_f32_e64 s[0:1], s52, v16
	s_nop 1
	v_cndmask_b32_e64 v16, v16, v17, s[0:1]
	v_rsq_f32_e32 v18, v16
	v_mad_i64_i32 v[16:17], s[24:25], v32, s49, v[150:151]
	v_lshl_add_u64 v[16:17], v[16:17], 0, v[120:121]
	v_mul_f32_e32 v19, 0x45800000, v18
	v_cndmask_b32_e64 v18, v18, v19, s[0:1]
	v_mul_f32_e32 v19, 0xbfb8aa3b, v18
	v_mul_f32_e32 v4, v4, v19
	v_mul_f32_e32 v5, v5, v19
	v_mul_f32_e32 v6, v6, v19
	v_mul_f32_e32 v7, v7, v19
	v_mul_f32_e32 v0, v0, v19
	v_mul_f32_e32 v1, v1, v19
	v_mul_f32_e32 v2, v2, v19
	v_mul_f32_e32 v3, v3, v19
	v_exp_f32_e32 v4, v4
	v_exp_f32_e32 v5, v5
	v_exp_f32_e32 v6, v6
	v_exp_f32_e32 v7, v7
	v_exp_f32_e32 v0, v0
	v_exp_f32_e32 v1, v1
	v_exp_f32_e32 v2, v2
	v_exp_f32_e32 v3, v3
	v_add_f32_e32 v4, 1.0, v4
	v_add_f32_e32 v5, 1.0, v5
	v_add_f32_e32 v6, 1.0, v6
	v_add_f32_e32 v7, 1.0, v7
	v_add_f32_e32 v19, 1.0, v0
	v_add_f32_e32 v20, 1.0, v1
	v_add_f32_e32 v21, 1.0, v2
	v_add_f32_e32 v22, 1.0, v3
	v_rcp_f32_e32 v0, v4
	v_rcp_f32_e32 v1, v5
	v_rcp_f32_e32 v2, v6
	v_rcp_f32_e32 v3, v7
	v_rcp_f32_e32 v4, v19
	v_rcp_f32_e32 v5, v20
	v_rcp_f32_e32 v6, v21
	v_rcp_f32_e32 v7, v22
	v_mul_f32_e32 v18, v18, v18
	v_pk_mul_f32 v[0:1], v[18:19], v[0:1] op_sel_hi:[0,1]
	v_pk_mul_f32 v[2:3], v[18:19], v[2:3] op_sel_hi:[0,1]
	v_pk_mul_f32 v[4:5], v[18:19], v[4:5] op_sel_hi:[0,1]
	v_pk_mul_f32 v[6:7], v[18:19], v[6:7] op_sel_hi:[0,1]
	v_pk_mul_f32 v[0:1], v[12:13], v[0:1]
	v_pk_mul_f32 v[2:3], v[14:15], v[2:3]
	v_pk_mul_f32 v[4:5], v[8:9], v[4:5]
	v_pk_mul_f32 v[6:7], v[10:11], v[6:7]
	v_cvt_pk_bf16_f32 v0, v0, v1
	v_cvt_pk_bf16_f32 v1, v2, v3
	v_cvt_pk_bf16_f32 v2, v4, v5
	v_cvt_pk_bf16_f32 v3, v6, v7
	s_mov_b64 s[0:1], -1
	global_store_dwordx4 v[16:17], v[0:3], off
	s_cbranch_vccnz .LBB0_1231
	s_andn2_b64 vcc, exec, s[8:9]
	s_cbranch_vccnz .LBB0_1230
	s_barrier
	s_branch .LBB0_1230

.LBB0_1323:
	v_lshl_add_u32 v150, s53, 8, v131
	v_ashrrev_i32_e32 v151, 31, v150
	v_lshl_or_b32 v148, s10, 8, v152
	v_lshlrev_b64 v[158:159], 11, v[150:151]
	v_ashrrev_i32_e32 v149, 31, v148
	v_lshl_add_u64 v[158:159], s[14:15], 0, v[158:159]
	v_lshl_add_u64 v[168:169], v[148:149], 1, v[158:159]
	global_load_dwordx4 v[160:163], v[168:169], off
	global_load_dwordx4 v[164:167], v[168:169], off offset:256
	s_mov_b64 s[100:101], 0x8000
	v_lshl_add_u64 v[232:233], v[168:169], 0, s[100:101]
	global_load_dwordx4 v[184:187], v[232:233], off
	global_load_dwordx4 v[188:191], v[232:233], off offset:256
	s_mov_b64 s[100:101], 0x10000
	v_lshl_add_u64 v[232:233], v[168:169], 0, s[100:101]
	global_load_dwordx4 v[192:195], v[232:233], off
	global_load_dwordx4 v[196:199], v[232:233], off offset:256
	s_mov_b64 s[100:101], 0x18000
	v_lshl_add_u64 v[232:233], v[168:169], 0, s[100:101]
	global_load_dwordx4 v[200:203], v[232:233], off
	global_load_dwordx4 v[204:207], v[232:233], off offset:256
	s_mov_b64 s[100:101], 0x40000
	v_lshl_add_u64 v[232:233], v[168:169], 0, s[100:101]
	global_load_dwordx4 v[208:211], v[232:233], off
	global_load_dwordx4 v[212:215], v[232:233], off offset:256
	s_mov_b64 s[100:101], 0x48000
	v_lshl_add_u64 v[232:233], v[168:169], 0, s[100:101]
	global_load_dwordx4 v[216:219], v[232:233], off
	global_load_dwordx4 v[220:223], v[232:233], off offset:256
	s_mov_b64 s[100:101], 0x50000
	v_lshl_add_u64 v[232:233], v[168:169], 0, s[100:101]
	global_load_dwordx4 v[224:227], v[232:233], off
	global_load_dwordx4 v[228:231], v[232:233], off offset:256
	s_mov_b64 s[100:101], 0x58000
	v_lshl_add_u64 v[232:233], v[168:169], 0, s[100:101]
	global_load_dwordx4 v[238:241], v[232:233], off
	global_load_dwordx4 v[242:245], v[232:233], off offset:256
	v_and_b32_e32 v158, 64, v156
	v_xor_b32_e32 v157, 16, v156
	v_add_u32_e32 v158, 64, v158
	v_xor_b32_e32 v159, 32, v156
	v_cmp_lt_i32_e32 vcc, v157, v158
	s_lshl_b32 s24, s10, 2
	s_ashr_i32 s25, s24, 31
	v_cndmask_b32_e32 v157, v156, v157, vcc
	v_cmp_lt_i32_e32 vcc, v159, v158
	v_lshlrev_b32_e32 v158, 2, v157
	s_waitcnt vmcnt(0)
	v_lshlrev_b32_e32 v170, 16, v160
	v_and_b32_e32 v171, 0xffff0000, v160
	v_lshlrev_b32_e32 v160, 16, v161
	v_and_b32_e32 v161, 0xffff0000, v161
	v_lshlrev_b32_e32 v172, 16, v162
	v_and_b32_e32 v173, 0xffff0000, v162
	v_lshlrev_b32_e32 v162, 16, v163
	v_and_b32_e32 v163, 0xffff0000, v163
	v_lshlrev_b32_e32 v174, 16, v164
	v_and_b32_e32 v175, 0xffff0000, v164
	v_lshlrev_b32_e32 v164, 16, v165
	v_and_b32_e32 v165, 0xffff0000, v165
	v_lshlrev_b32_e32 v176, 16, v166
	v_and_b32_e32 v177, 0xffff0000, v166
	v_lshlrev_b32_e32 v166, 16, v167
	v_and_b32_e32 v167, 0xffff0000, v167
	v_pk_add_f32 v[124:125], v[124:125], v[170:171]
	v_pk_add_f32 v[126:127], v[126:127], v[160:161]
	v_pk_add_f32 v[120:121], v[120:121], v[172:173]
	v_pk_add_f32 v[122:123], v[122:123], v[162:163]
	v_pk_add_f32 v[116:117], v[116:117], v[174:175]
	v_pk_add_f32 v[118:119], v[118:119], v[164:165]
	v_pk_add_f32 v[160:161], v[112:113], v[176:177]
	v_pk_add_f32 v[162:163], v[114:115], v[166:167]
	v_cndmask_b32_e32 v159, v156, v159, vcc
	v_cvt_pk_bf16_f32 v112, v124, v125
	v_cvt_pk_bf16_f32 v113, v126, v127
	v_pk_mul_f32 v[114:115], v[124:125], v[124:125]
	v_pk_mul_f32 v[124:125], v[126:127], v[126:127]
	v_pk_mul_f32 v[126:127], v[120:121], v[120:121]
	v_pk_mul_f32 v[164:165], v[122:123], v[122:123]
	v_pk_mul_f32 v[166:167], v[116:117], v[116:117]
	v_pk_mul_f32 v[170:171], v[118:119], v[118:119]
	v_pk_mul_f32 v[172:173], v[160:161], v[160:161]
	v_pk_mul_f32 v[174:175], v[162:163], v[162:163]
	v_lshlrev_b32_e32 v157, 2, v159
	v_add_f32_e32 v159, v174, v175
	v_add_f32_e32 v172, v172, v173
	v_add_f32_e32 v170, v170, v171
	v_add_f32_e32 v166, v166, v167
	v_add_f32_e32 v164, v164, v165
	v_add_f32_e32 v126, v126, v127
	v_add_f32_e32 v124, v124, v125
	v_add_f32_e32 v114, v114, v115
	v_add_f32_e32 v115, v172, v159
	v_add_f32_e32 v125, v166, v170
	v_add_f32_e32 v126, v126, v164
	v_add_f32_e32 v114, v114, v124
	v_add_f32_e32 v115, v125, v115
	v_add_f32_e32 v114, v114, v126
	v_add_f32_e32 v124, v114, v115
	v_mov_b32_e32 v125, v124
	s_nop 1
	v_permlane16_swap_b32_e32 v124, v125
	v_cvt_pk_bf16_f32 v114, v120, v121
	v_cvt_pk_bf16_f32 v115, v122, v123
	global_store_dwordx4 v[168:169], v[112:115], off
	s_waitcnt lgkmcnt(0)
	s_nop 0
	v_add_f32_e32 v112, v124, v125
	v_mov_b32_e32 v113, v112
	s_nop 1
	v_permlane32_swap_b32_e32 v112, v113
	v_cvt_pk_bf16_f32 v114, v116, v117
	v_cvt_pk_bf16_f32 v115, v118, v119
	v_cvt_pk_bf16_f32 v116, v160, v161
	v_cvt_pk_bf16_f32 v117, v162, v163
	global_store_dwordx4 v[168:169], v[114:117], off offset:256
	s_and_saveexec_b64 s[26:27], s[4:5]
	s_cbranch_execz .LBB0_1325
	v_lshlrev_b64 v[114:115], 6, v[150:151]
	v_lshl_add_u64 v[114:115], s[16:17], 0, v[114:115]
	v_lshl_add_u64 v[114:115], s[24:25], 2, v[114:115]
	s_lshl_b32 s10, s40, 2
	v_lshl_add_u64 v[114:115], v[114:115], 0, s[10:11]
	s_waitcnt lgkmcnt(0)
	v_add_f32_e32 v112, v112, v113
	global_store_dword v[114:115], v112, off
.LBB0_1325:
	s_or_b64 exec, exec, s[26:27]
	v_or_b32_e32 v112, 16, v150
	s_waitcnt lgkmcnt(0)
	v_ashrrev_i32_e32 v113, 31, v112
	v_lshlrev_b64 v[114:115], 11, v[112:113]
	v_lshl_add_u64 v[114:115], s[14:15], 0, v[114:115]
	v_lshl_add_u64 v[122:123], v[148:149], 1, v[114:115]
	s_nop 1
	v_mov_b32_e32 v114, v184
	v_mov_b32_e32 v115, v185
	v_mov_b32_e32 v116, v186
	v_mov_b32_e32 v117, v187
	v_mov_b32_e32 v118, v188
	v_mov_b32_e32 v119, v189
	v_mov_b32_e32 v120, v190
	v_mov_b32_e32 v121, v191
	v_lshlrev_b32_e32 v124, 16, v114
	v_and_b32_e32 v125, 0xffff0000, v114
	v_lshlrev_b32_e32 v114, 16, v115
	v_and_b32_e32 v115, 0xffff0000, v115
	v_lshlrev_b32_e32 v126, 16, v116
	v_and_b32_e32 v127, 0xffff0000, v116
	v_lshlrev_b32_e32 v116, 16, v117
	v_and_b32_e32 v117, 0xffff0000, v117
	v_lshlrev_b32_e32 v160, 16, v118
	v_and_b32_e32 v161, 0xffff0000, v118
	v_lshlrev_b32_e32 v118, 16, v119
	v_and_b32_e32 v119, 0xffff0000, v119
	v_lshlrev_b32_e32 v162, 16, v120
	v_and_b32_e32 v163, 0xffff0000, v120
	v_lshlrev_b32_e32 v120, 16, v121
	v_and_b32_e32 v121, 0xffff0000, v121
	v_pk_add_f32 v[108:109], v[108:109], v[124:125]
	v_pk_add_f32 v[110:111], v[110:111], v[114:115]
	v_pk_add_f32 v[104:105], v[104:105], v[126:127]
	v_pk_add_f32 v[106:107], v[106:107], v[116:117]
	v_pk_add_f32 v[100:101], v[100:101], v[160:161]
	v_pk_add_f32 v[102:103], v[102:103], v[118:119]
	v_pk_add_f32 v[114:115], v[96:97], v[162:163]
	v_pk_add_f32 v[116:117], v[98:99], v[120:121]
	v_cvt_pk_bf16_f32 v96, v108, v109
	v_cvt_pk_bf16_f32 v97, v110, v111
	v_pk_mul_f32 v[98:99], v[108:109], v[108:109]
	v_pk_mul_f32 v[108:109], v[110:111], v[110:111]
	v_pk_mul_f32 v[110:111], v[104:105], v[104:105]
	v_pk_mul_f32 v[118:119], v[106:107], v[106:107]
	v_pk_mul_f32 v[120:121], v[100:101], v[100:101]
	v_pk_mul_f32 v[124:125], v[102:103], v[102:103]
	v_pk_mul_f32 v[126:127], v[114:115], v[114:115]
	v_pk_mul_f32 v[160:161], v[116:117], v[116:117]
	v_add_f32_e32 v126, v126, v127
	v_add_f32_e32 v151, v160, v161
	v_add_f32_e32 v124, v124, v125
	v_add_f32_e32 v120, v120, v121
	v_add_f32_e32 v118, v118, v119
	v_add_f32_e32 v110, v110, v111
	v_add_f32_e32 v108, v108, v109
	v_add_f32_e32 v98, v98, v99
	v_add_f32_e32 v99, v126, v151
	v_add_f32_e32 v109, v120, v124
	v_add_f32_e32 v110, v110, v118
	v_add_f32_e32 v98, v98, v108
	v_add_f32_e32 v99, v109, v99
	v_add_f32_e32 v98, v98, v110
	v_add_f32_e32 v108, v98, v99
	v_mov_b32_e32 v109, v108
	s_nop 1
	v_permlane16_swap_b32_e32 v108, v109
	v_cvt_pk_bf16_f32 v98, v104, v105
	v_cvt_pk_bf16_f32 v99, v106, v107
	global_store_dwordx4 v[122:123], v[96:99], off
	s_waitcnt lgkmcnt(0)
	s_nop 0
	v_add_f32_e32 v96, v108, v109
	v_mov_b32_e32 v97, v96
	s_nop 1
	v_permlane32_swap_b32_e32 v96, v97
	v_cvt_pk_bf16_f32 v98, v100, v101
	v_cvt_pk_bf16_f32 v99, v102, v103
	v_cvt_pk_bf16_f32 v100, v114, v115
	v_cvt_pk_bf16_f32 v101, v116, v117
	global_store_dwordx4 v[122:123], v[98:101], off offset:256
	s_and_saveexec_b64 s[26:27], s[4:5]
	s_cbranch_execz .LBB0_1327
	v_lshlrev_b64 v[98:99], 6, v[112:113]
	v_lshl_add_u64 v[98:99], s[16:17], 0, v[98:99]
	v_lshl_add_u64 v[98:99], s[24:25], 2, v[98:99]
	s_lshl_b32 s10, s40, 2
	v_lshl_add_u64 v[98:99], v[98:99], 0, s[10:11]
	s_waitcnt lgkmcnt(0)
	v_add_f32_e32 v96, v96, v97
	global_store_dword v[98:99], v96, off
